# strategy 7 (cross-lane movement without LDS): fused-LN epilogue exchanges the row statistics between lane halves with v_permlane32_swap instead of four ds_bpermute round trips
# baseline (speedup 1.0000x reference)
; #define RL_LOAD(XV, G) { constexpr int mt__ = (G) >> 2, half__ = ((G) >> 1) & 1, nt__ = (G) & 1; \
;     _Pragma("unroll") for (int gq = 0; gq < 4; ++gq) XV[gq] = *(const f32x4*)(xin + rbase + (size_t)mt__ * 32 * 1024 + half__ * 64 + nt__ * 32 + 4 * gq); }
; #define RL_FOLD(XV, G, SM, SQ) { constexpr int mt__ = (G) >> 2, half__ = ((G) >> 1) & 1, nt__ = (G) & 1; \
;     _Pragma("unroll") for (int gq = 0; gq < 4; ++gq) _Pragma("unroll") for (int jj = 0; jj < 4; ++jj) { \
;       const float y = ALPHA * XV[gq][jj] + acc[half__][nt__][mt__][4 * gq + jj]; acc[half__][nt__][mt__][4 * gq + jj] = y; SM += y; SQ += y * y; } }
; #define SB __builtin_amdgcn_sched_barrier(0)
;   DI void full(const int mt_, const int nt_, f32x16 (&acc)[2][2][2], const int tw, const int fw, const int r, const int hh, char* lds, const int tid) const {
;     ...
;     float sm0 = 0.f, sq0 = 0.f, sm1 = 0.f, sq1 = 0.f;
;     RL_LOAD(xa, 0); RL_LOAD(xc, 1); RL_LOAD(xe, 2); SB;
;     RL_FOLD(xa, 0, sm0, sq0); SB; RL_LOAD(xa, 3); SB;
;     RL_FOLD(xc, 1, sm0, sq0); SB; RL_LOAD(xc, 4); SB;
;     RL_FOLD(xe, 2, sm0, sq0); SB; RL_LOAD(xe, 5); SB;
;     RL_FOLD(xa, 3, sm0, sq0); SB; RL_LOAD(xa, 6); SB;
;     RL_FOLD(xc, 4, sm1, sq1); SB; RL_LOAD(xc, 7); SB;
;     RL_FOLD(xe, 5, sm1, sq1); SB;
;     RL_FOLD(xa, 6, sm1, sq1); SB;
;     RL_FOLD(xc, 7, sm1, sq1);
.Lkexit_1:
	v_mov_b32_e32 v184, v192
	s_waitcnt vmcnt(1)
	v_ashrrev_i32_e32 v130, 1, v184
	v_and_b32_e32 v223, 0xdf, v184
	v_and_b32_e32 v182, 0xffffff80, v130
	v_or_b32_e32 v0, s4, v223
	v_ashrrev_i32_e32 v183, 31, v182
	v_bfe_u32 v224, v184, 5, 1
	v_lshl_add_u64 v[130:131], v[182:183], 2, s[18:19]
	v_lshlrev_b64 v[132:133], 12, v[0:1]
	v_lshl_add_u64 v[130:131], v[130:131], 0, v[132:133]
	v_lshlrev_b32_e32 v132, 6, v224
	v_mov_b32_e32 v133, v1
	v_lshl_add_u64 v[186:187], v[130:131], 0, v[132:133]
	global_load_dwordx4 v[130:133], v[186:187], off offset:48
	global_load_dwordx4 v[134:137], v[186:187], off offset:32
	global_load_dwordx4 v[138:141], v[186:187], off offset:16
	global_load_dwordx4 v[142:145], v[186:187], off
	global_load_dwordx4 v[194:197], v[186:187], off offset:176
	global_load_dwordx4 v[202:205], v[186:187], off offset:160
	global_load_dwordx4 v[226:229], v[186:187], off offset:144
	global_load_dwordx4 v[146:149], v[186:187], off offset:128
	global_load_dwordx4 v[230:233], v[186:187], off offset:304
	global_load_dwordx4 v[234:237], v[186:187], off offset:288
	global_load_dwordx4 v[238:241], v[186:187], off offset:272
	global_load_dwordx4 v[242:245], v[186:187], off offset:256
	s_waitcnt vmcnt(8)
	v_pk_fma_f32 v[178:179], v[142:143], s[0:1], v[114:115] op_sel_hi:[1,0,1]
	v_pk_fma_f32 v[180:181], v[144:145], s[0:1], v[116:117] op_sel_hi:[1,0,1]
	v_add_f32_e32 v114, 0, v178
	v_add_f32_e32 v142, v179, v114
	v_mul_f32_e32 v114, v179, v179
	v_pk_fma_f32 v[114:115], v[178:179], v[178:179], v[114:115] op_sel_hi:[1,1,0]
	v_add_f32_e32 v116, v180, v142
	v_pk_fma_f32 v[114:115], v[180:181], v[180:181], v[114:115]
	v_add_f32_e32 v117, v181, v116
	v_mul_f32_e32 v116, v181, v181
	v_pk_fma_f32 v[158:159], v[138:139], s[0:1], v[118:119] op_sel_hi:[1,0,1]
	v_pk_add_f32 v[114:115], v[116:117], v[114:115] op_sel_hi:[0,1]
	v_add_f32_e32 v116, v158, v117
	v_pk_fma_f32 v[114:115], v[158:159], v[158:159], v[114:115]
	v_add_f32_e32 v117, v159, v116
	v_mul_f32_e32 v116, v159, v159
	v_pk_fma_f32 v[160:161], v[140:141], s[0:1], v[120:121] op_sel_hi:[1,0,1]
	v_pk_add_f32 v[114:115], v[116:117], v[114:115] op_sel_hi:[0,1]
	v_add_f32_e32 v116, v160, v117
	v_pk_fma_f32 v[114:115], v[160:161], v[160:161], v[114:115]
	v_add_f32_e32 v117, v161, v116
	v_mul_f32_e32 v116, v161, v161
	v_pk_fma_f32 v[154:155], v[134:135], s[0:1], v[122:123] op_sel_hi:[1,0,1]
	v_pk_add_f32 v[114:115], v[116:117], v[114:115] op_sel_hi:[0,1]
	v_add_f32_e32 v116, v154, v117
	v_pk_fma_f32 v[114:115], v[154:155], v[154:155], v[114:115]
	v_add_f32_e32 v117, v155, v116
	v_mul_f32_e32 v116, v155, v155
	v_pk_fma_f32 v[156:157], v[136:137], s[0:1], v[124:125] op_sel_hi:[1,0,1]
	v_pk_add_f32 v[114:115], v[116:117], v[114:115] op_sel_hi:[0,1]
	v_add_f32_e32 v116, v156, v117
	v_pk_fma_f32 v[114:115], v[156:157], v[156:157], v[114:115]
	v_add_f32_e32 v124, v157, v116
	v_mul_f32_e32 v116, v157, v157
	v_pk_add_f32 v[114:115], v[116:117], v[114:115] op_sel_hi:[0,1]
	v_pk_fma_f32 v[152:153], v[130:131], s[0:1], v[126:127] op_sel_hi:[1,0,1]
	v_pk_fma_f32 v[150:151], v[132:133], s[0:1], v[128:129] op_sel_hi:[1,0,1]
	v_pk_fma_f32 v[114:115], v[152:153], v[152:153], v[114:115]
	v_mul_f32_e32 v116, v153, v153
	v_pk_add_f32 v[114:115], v[116:117], v[114:115] op_sel_hi:[0,1]
	v_pk_fma_f32 v[114:115], v[150:151], v[150:151], v[114:115]
	v_mul_f32_e32 v116, v151, v151
	v_pk_add_f32 v[118:119], v[116:117], v[114:115] op_sel_hi:[0,1]
	global_load_dwordx4 v[114:117], v[186:187], off offset:432
	global_load_dwordx4 v[246:249], v[186:187], off offset:416
	global_load_dwordx4 v[250:253], v[186:187], off offset:400
	global_load_dwordx4 v[120:123], v[186:187], off offset:384
	v_add_f32_e32 v124, v152, v124
	v_add_f32_e32 v124, v153, v124
	v_add_f32_e32 v124, v150, v124
	v_add_f32_e32 v124, v151, v124
	s_waitcnt vmcnt(8)
	v_pk_fma_f32 v[144:145], v[146:147], s[0:1], v[98:99] op_sel_hi:[1,0,1]
	v_pk_fma_f32 v[148:149], v[148:149], s[0:1], v[100:101] op_sel_hi:[1,0,1]
	v_add_f32_e32 v124, v144, v124
	v_pk_fma_f32 v[98:99], v[144:145], v[144:145], v[118:119]
	v_add_f32_e32 v119, v145, v124
	v_mul_f32_e32 v118, v145, v145
	v_pk_add_f32 v[98:99], v[118:119], v[98:99] op_sel_hi:[0,1]
	v_add_f32_e32 v100, v148, v119
	v_pk_fma_f32 v[98:99], v[148:149], v[148:149], v[98:99]
	v_add_f32_e32 v101, v149, v100
	v_mul_f32_e32 v100, v149, v149
	v_pk_fma_f32 v[138:139], v[226:227], s[0:1], v[102:103] op_sel_hi:[1,0,1]
	v_pk_add_f32 v[98:99], v[100:101], v[98:99] op_sel_hi:[0,1]
	v_add_f32_e32 v100, v138, v101
	v_pk_fma_f32 v[98:99], v[138:139], v[138:139], v[98:99]
	v_add_f32_e32 v101, v139, v100
	v_mul_f32_e32 v100, v139, v139
	v_pk_fma_f32 v[146:147], v[228:229], s[0:1], v[104:105] op_sel_hi:[1,0,1]
	v_pk_add_f32 v[98:99], v[100:101], v[98:99] op_sel_hi:[0,1]
	v_add_f32_e32 v100, v146, v101
	v_pk_fma_f32 v[98:99], v[146:147], v[146:147], v[98:99]
	v_add_f32_e32 v101, v147, v100
	v_mul_f32_e32 v100, v147, v147
	v_pk_fma_f32 v[130:131], v[202:203], s[0:1], v[106:107] op_sel_hi:[1,0,1]
	v_pk_add_f32 v[98:99], v[100:101], v[98:99] op_sel_hi:[0,1]
	v_add_f32_e32 v100, v130, v101
	v_pk_fma_f32 v[98:99], v[130:131], v[130:131], v[98:99]
	v_add_f32_e32 v101, v131, v100
	v_mul_f32_e32 v100, v131, v131
	v_pk_fma_f32 v[140:141], v[204:205], s[0:1], v[108:109] op_sel_hi:[1,0,1]
	v_pk_add_f32 v[98:99], v[100:101], v[98:99] op_sel_hi:[0,1]
	v_add_f32_e32 v100, v140, v101
	v_pk_fma_f32 v[98:99], v[140:141], v[140:141], v[98:99]
	v_add_f32_e32 v106, v141, v100
	v_mul_f32_e32 v100, v141, v141
	v_pk_add_f32 v[102:103], v[100:101], v[98:99] op_sel_hi:[0,1]
	v_pk_fma_f32 v[124:125], v[194:195], s[0:1], v[110:111] op_sel_hi:[1,0,1]
	v_pk_fma_f32 v[134:135], v[196:197], s[0:1], v[112:113] op_sel_hi:[1,0,1]
	v_add_co_u32_e32 v188, vcc, s91, v186
	s_mov_b64 s[20:21], 0x20000
	s_nop 0
	v_addc_co_u32_e32 v189, vcc, 0, v187, vcc
	v_lshl_add_u64 v[104:105], v[186:187], 0, s[20:21]
	global_load_dwordx4 v[194:197], v[188:189], off
	global_load_dwordx4 v[98:101], v[104:105], off offset:48
	global_load_dwordx4 v[202:205], v[104:105], off offset:32
	global_load_dwordx4 v[226:229], v[104:105], off offset:16
	v_add_f32_e32 v104, v124, v106
	v_pk_fma_f32 v[102:103], v[124:125], v[124:125], v[102:103]
	v_add_f32_e32 v105, v125, v104
	v_mul_f32_e32 v104, v125, v125
	v_pk_add_f32 v[102:103], v[104:105], v[102:103] op_sel_hi:[0,1]
	v_add_f32_e32 v104, v134, v105
	v_pk_fma_f32 v[102:103], v[134:135], v[134:135], v[102:103]
	v_add_f32_e32 v105, v135, v104
	v_mul_f32_e32 v104, v135, v135
	v_pk_add_f32 v[102:103], v[104:105], v[102:103] op_sel_hi:[0,1]
	s_waitcnt vmcnt(8)
; #define RL_LOAD(XV, G) { constexpr int mt__ = (G) >> 2, half__ = ((G) >> 1) & 1, nt__ = (G) & 1; \
;     _Pragma("unroll") for (int gq = 0; gq < 4; ++gq) XV[gq] = *(const f32x4*)(xin + rbase + (size_t)mt__ * 32 * 1024 + half__ * 64 + nt__ * 32 + 4 * gq); }
; #define RL_FOLD(XV, G, SM, SQ) { constexpr int mt__ = (G) >> 2, half__ = ((G) >> 1) & 1, nt__ = (G) & 1; \
;     _Pragma("unroll") for (int gq = 0; gq < 4; ++gq) _Pragma("unroll") for (int jj = 0; jj < 4; ++jj) { \
;       const float y = ALPHA * XV[gq][jj] + acc[half__][nt__][mt__][4 * gq + jj]; acc[half__][nt__][mt__][4 * gq + jj] = y; SM += y; SQ += y * y; } }
; #define SB __builtin_amdgcn_sched_barrier(0)
;   DI void full(const int mt_, const int nt_, f32x16 (&acc)[2][2][2], const int tw, const int fw, const int r, const int hh, char* lds, const int tid) const {
;     ...
;     float sm0 = 0.f, sq0 = 0.f, sm1 = 0.f, sq1 = 0.f;
;     RL_LOAD(xa, 0); RL_LOAD(xc, 1); RL_LOAD(xe, 2); SB;
;     RL_FOLD(xa, 0, sm0, sq0); SB; RL_LOAD(xa, 3); SB;
;     RL_FOLD(xc, 1, sm0, sq0); SB; RL_LOAD(xc, 4); SB;
;     RL_FOLD(xe, 2, sm0, sq0); SB; RL_LOAD(xe, 5); SB;
;     RL_FOLD(xa, 3, sm0, sq0); SB; RL_LOAD(xa, 6); SB;
;     RL_FOLD(xc, 4, sm1, sq1); SB; RL_LOAD(xc, 7); SB;
;     RL_FOLD(xe, 5, sm1, sq1); SB;
;     RL_FOLD(xa, 6, sm1, sq1); SB;
;     RL_FOLD(xc, 7, sm1, sq1);
	v_pk_fma_f32 v[132:133], v[242:243], s[0:1], v[82:83] op_sel_hi:[1,0,1]
	v_pk_fma_f32 v[142:143], v[244:245], s[0:1], v[84:85] op_sel_hi:[1,0,1]
	v_add_f32_e32 v104, v132, v105
	v_pk_fma_f32 v[82:83], v[132:133], v[132:133], v[102:103]
	v_add_f32_e32 v103, v133, v104
	v_mul_f32_e32 v102, v133, v133
	v_pk_add_f32 v[82:83], v[102:103], v[82:83] op_sel_hi:[0,1]
	v_add_f32_e32 v84, v142, v103
	v_pk_fma_f32 v[82:83], v[142:143], v[142:143], v[82:83]
	v_add_f32_e32 v85, v143, v84
	v_mul_f32_e32 v84, v143, v143
	v_pk_fma_f32 v[126:127], v[238:239], s[0:1], v[86:87] op_sel_hi:[1,0,1]
	v_pk_add_f32 v[82:83], v[84:85], v[82:83] op_sel_hi:[0,1]
	v_add_f32_e32 v84, v126, v85
	v_pk_fma_f32 v[82:83], v[126:127], v[126:127], v[82:83]
	v_add_f32_e32 v85, v127, v84
	v_mul_f32_e32 v84, v127, v127
	v_pk_fma_f32 v[136:137], v[240:241], s[0:1], v[88:89] op_sel_hi:[1,0,1]
	v_pk_add_f32 v[82:83], v[84:85], v[82:83] op_sel_hi:[0,1]
	v_add_f32_e32 v84, v136, v85
	v_pk_fma_f32 v[82:83], v[136:137], v[136:137], v[82:83]
	v_add_f32_e32 v85, v137, v84
	v_mul_f32_e32 v84, v137, v137
	v_pk_fma_f32 v[112:113], v[234:235], s[0:1], v[90:91] op_sel_hi:[1,0,1]
	v_pk_add_f32 v[82:83], v[84:85], v[82:83] op_sel_hi:[0,1]
	v_add_f32_e32 v84, v112, v85
	v_pk_fma_f32 v[82:83], v[112:113], v[112:113], v[82:83]
	v_add_f32_e32 v85, v113, v84
	v_mul_f32_e32 v84, v113, v113
	v_pk_fma_f32 v[128:129], v[236:237], s[0:1], v[92:93] op_sel_hi:[1,0,1]
	v_pk_add_f32 v[82:83], v[84:85], v[82:83] op_sel_hi:[0,1]
	v_add_f32_e32 v84, v128, v85
	v_pk_fma_f32 v[82:83], v[128:129], v[128:129], v[82:83]
	v_add_f32_e32 v90, v129, v84
	v_mul_f32_e32 v84, v129, v129
	v_pk_add_f32 v[86:87], v[84:85], v[82:83] op_sel_hi:[0,1]
	v_pk_fma_f32 v[106:107], v[230:231], s[0:1], v[94:95] op_sel_hi:[1,0,1]
	v_pk_fma_f32 v[118:119], v[232:233], s[0:1], v[96:97] op_sel_hi:[1,0,1]
	s_mov_b64 s[20:21], 0x20080
	v_lshl_add_u64 v[88:89], v[186:187], 0, s[20:21]
	global_load_dwordx4 v[82:85], v[88:89], off offset:48
	global_load_dwordx4 v[230:233], v[88:89], off offset:32
	global_load_dwordx4 v[234:237], v[188:189], off offset:128
	global_load_dwordx4 v[238:241], v[88:89], off offset:16
	v_add_f32_e32 v88, v106, v90
	v_pk_fma_f32 v[86:87], v[106:107], v[106:107], v[86:87]
	v_add_f32_e32 v89, v107, v88
	v_mul_f32_e32 v88, v107, v107
	v_pk_add_f32 v[86:87], v[88:89], v[86:87] op_sel_hi:[0,1]
	v_add_f32_e32 v88, v118, v89
	v_pk_fma_f32 v[86:87], v[118:119], v[118:119], v[86:87]
	v_add_f32_e32 v89, v119, v88
	v_mul_f32_e32 v88, v119, v119
	v_pk_add_f32 v[86:87], v[88:89], v[86:87] op_sel_hi:[0,1]
	s_waitcnt vmcnt(8)
	v_pk_fma_f32 v[104:105], v[120:121], s[0:1], v[50:51] op_sel_hi:[1,0,1]
	v_pk_fma_f32 v[122:123], v[122:123], s[0:1], v[52:53] op_sel_hi:[1,0,1]
	v_add_f32_e32 v88, v104, v89
	v_pk_fma_f32 v[50:51], v[104:105], v[104:105], v[86:87]
	v_add_f32_e32 v87, v105, v88
	v_mul_f32_e32 v86, v105, v105
	v_add_f32_e32 v52, v122, v87
	v_pk_add_f32 v[50:51], v[86:87], v[50:51] op_sel_hi:[0,1]
	v_add_f32_e32 v52, v123, v52
	v_pk_fma_f32 v[102:103], v[250:251], s[0:1], v[54:55] op_sel_hi:[1,0,1]
	v_pk_fma_f32 v[50:51], v[122:123], v[122:123], v[50:51]
	v_add_f32_e32 v55, v102, v52
	v_mul_f32_e32 v54, v123, v123
	v_mov_b32_e32 v52, v102
	v_mov_b32_e32 v53, v123
	v_pk_add_f32 v[50:51], v[54:55], v[50:51] op_sel_hi:[0,1]
	v_pk_fma_f32 v[50:51], v[52:53], v[52:53], v[50:51]
	v_add_f32_e32 v52, v103, v55
	v_pk_fma_f32 v[120:121], v[252:253], s[0:1], v[56:57] op_sel_hi:[1,0,1]
	v_mul_f32_e32 v54, v103, v103
	v_add_f32_e32 v55, v120, v52
	v_mov_b32_e32 v52, v120
	v_mov_b32_e32 v53, v103
	v_pk_add_f32 v[50:51], v[54:55], v[50:51] op_sel_hi:[0,1]
	v_pk_fma_f32 v[50:51], v[52:53], v[52:53], v[50:51]
	v_add_f32_e32 v52, v121, v55
	v_pk_fma_f32 v[94:95], v[246:247], s[0:1], v[58:59] op_sel_hi:[1,0,1]
	v_mul_f32_e32 v54, v121, v121
	v_add_f32_e32 v55, v94, v52
	v_mov_b32_e32 v52, v94
	v_mov_b32_e32 v53, v121
	v_pk_add_f32 v[50:51], v[54:55], v[50:51] op_sel_hi:[0,1]
	v_pk_fma_f32 v[50:51], v[52:53], v[52:53], v[50:51]
	v_add_f32_e32 v52, v95, v55
	v_pk_fma_f32 v[108:109], v[248:249], s[0:1], v[60:61] op_sel_hi:[1,0,1]
	v_mul_f32_e32 v54, v95, v95
	v_add_f32_e32 v55, v108, v52
	v_mov_b32_e32 v52, v108
	v_mov_b32_e32 v53, v95
	v_pk_add_f32 v[50:51], v[54:55], v[50:51] op_sel_hi:[0,1]
	v_pk_fma_f32 v[50:51], v[52:53], v[52:53], v[50:51]
	v_pk_fma_f32 v[96:97], v[114:115], s[0:1], v[62:63] op_sel_hi:[1,0,1]
	v_mul_f32_e32 v54, v109, v109
	v_pk_fma_f32 v[110:111], v[116:117], s[0:1], v[64:65] op_sel_hi:[1,0,1]
	v_add_f32_e32 v58, v109, v55
	v_pk_add_f32 v[50:51], v[54:55], v[50:51] op_sel_hi:[0,1]
	v_mov_b32_e32 v54, v110
	v_mov_b32_e32 v55, v97
	v_mov_b32_e32 v52, v96
	v_mov_b32_e32 v53, v109
	v_pk_mul_f32 v[114:115], v[110:111], v[110:111]
	s_mov_b64 s[20:21], 0x20100
	v_lshl_add_u64 v[56:57], v[186:187], 0, s[20:21]
	global_load_dwordx4 v[242:245], v[56:57], off offset:48
	global_load_dwordx4 v[246:249], v[56:57], off offset:32
	global_load_dwordx4 v[250:253], v[188:189], off offset:256
	global_load_dwordx4 v[166:169], v[56:57], off offset:16
	v_add_f32_e32 v56, v96, v58
	v_add_f32_e32 v56, v97, v56
	v_add_f32_e32 v114, v110, v56
	s_waitcnt vmcnt(11)
	v_pk_fma_f32 v[90:91], v[194:195], s[0:1], v[66:67] op_sel_hi:[1,0,1]
	v_pk_fma_f32 v[92:93], v[196:197], s[0:1], v[68:69] op_sel_hi:[1,0,1]
	v_add_f32_e32 v56, 0, v90
	v_add_f32_e32 v58, v91, v56
	v_mul_f32_e32 v56, v91, v91
	v_pk_fma_f32 v[56:57], v[90:91], v[90:91], v[56:57] op_sel_hi:[1,1,0]
	v_add_f32_e32 v58, v92, v58
	v_pk_fma_f32 v[56:57], v[92:93], v[92:93], v[56:57]
	v_add_f32_e32 v59, v93, v58
	v_mul_f32_e32 v58, v93, v93
	s_waitcnt vmcnt(8)
; #define RL_LOAD(XV, G) { constexpr int mt__ = (G) >> 2, half__ = ((G) >> 1) & 1, nt__ = (G) & 1; \
;     _Pragma("unroll") for (int gq = 0; gq < 4; ++gq) XV[gq] = *(const f32x4*)(xin + rbase + (size_t)mt__ * 32 * 1024 + half__ * 64 + nt__ * 32 + 4 * gq); }
; #define RL_FOLD(XV, G, SM, SQ) { constexpr int mt__ = (G) >> 2, half__ = ((G) >> 1) & 1, nt__ = (G) & 1; \
;     _Pragma("unroll") for (int gq = 0; gq < 4; ++gq) _Pragma("unroll") for (int jj = 0; jj < 4; ++jj) { \
;       const float y = ALPHA * XV[gq][jj] + acc[half__][nt__][mt__][4 * gq + jj]; acc[half__][nt__][mt__][4 * gq + jj] = y; SM += y; SQ += y * y; } }
; #define SB __builtin_amdgcn_sched_barrier(0)
;   DI void full(const int mt_, const int nt_, f32x16 (&acc)[2][2][2], const int tw, const int fw, const int r, const int hh, char* lds, const int tid) const {
;     ...
;     float sm0 = 0.f, sq0 = 0.f, sm1 = 0.f, sq1 = 0.f;
;     RL_LOAD(xa, 0); RL_LOAD(xc, 1); RL_LOAD(xe, 2); SB;
;     RL_FOLD(xa, 0, sm0, sq0); SB; RL_LOAD(xa, 3); SB;
;     RL_FOLD(xc, 1, sm0, sq0); SB; RL_LOAD(xc, 4); SB;
;     RL_FOLD(xe, 2, sm0, sq0); SB; RL_LOAD(xe, 5); SB;
;     RL_FOLD(xa, 3, sm0, sq0); SB; RL_LOAD(xa, 6); SB;
;     RL_FOLD(xc, 4, sm1, sq1); SB; RL_LOAD(xc, 7); SB;
;     RL_FOLD(xe, 5, sm1, sq1); SB;
;     RL_FOLD(xa, 6, sm1, sq1); SB;
;     RL_FOLD(xc, 7, sm1, sq1);
	v_pk_fma_f32 v[86:87], v[226:227], s[0:1], v[70:71] op_sel_hi:[1,0,1]
	v_pk_add_f32 v[56:57], v[58:59], v[56:57] op_sel_hi:[0,1]
	v_add_f32_e32 v58, v86, v59
	v_pk_fma_f32 v[56:57], v[86:87], v[86:87], v[56:57]
	v_add_f32_e32 v59, v87, v58
	v_mul_f32_e32 v58, v87, v87
	v_pk_fma_f32 v[88:89], v[228:229], s[0:1], v[72:73] op_sel_hi:[1,0,1]
	v_pk_add_f32 v[56:57], v[58:59], v[56:57] op_sel_hi:[0,1]
	v_add_f32_e32 v58, v88, v59
	v_pk_fma_f32 v[56:57], v[88:89], v[88:89], v[56:57]
	v_add_f32_e32 v59, v89, v58
	v_mul_f32_e32 v58, v89, v89
	v_pk_fma_f32 v[70:71], v[202:203], s[0:1], v[74:75] op_sel_hi:[1,0,1]
	v_pk_add_f32 v[56:57], v[58:59], v[56:57] op_sel_hi:[0,1]
	v_add_f32_e32 v58, v70, v59
	v_pk_fma_f32 v[56:57], v[70:71], v[70:71], v[56:57]
	v_add_f32_e32 v59, v71, v58
	v_mul_f32_e32 v58, v71, v71
	v_pk_fma_f32 v[72:73], v[204:205], s[0:1], v[76:77] op_sel_hi:[1,0,1]
	v_pk_add_f32 v[56:57], v[58:59], v[56:57] op_sel_hi:[0,1]
	v_add_f32_e32 v58, v72, v59
	v_pk_fma_f32 v[56:57], v[72:73], v[72:73], v[56:57]
	v_add_f32_e32 v59, v73, v58
	v_mul_f32_e32 v58, v73, v73
	v_pk_fma_f32 v[50:51], v[52:53], v[52:53], v[50:51]
	v_mul_f32_e32 v52, v97, v97
	v_pk_add_f32 v[56:57], v[58:59], v[56:57] op_sel_hi:[0,1]
	v_pk_fma_f32 v[68:69], v[98:99], s[0:1], v[78:79] op_sel_hi:[1,0,1]
	v_pk_fma_f32 v[66:67], v[100:101], s[0:1], v[80:81] op_sel_hi:[1,0,1]
	v_pk_add_f32 v[50:51], v[52:53], v[50:51] op_sel_hi:[0,1]
	v_pk_fma_f32 v[74:75], v[54:55], v[54:55], v[50:51]
	s_mov_b64 s[20:21], 0x20180
	v_lshl_add_u64 v[54:55], v[186:187], 0, s[20:21]
	global_load_dwordx4 v[50:53], v[54:55], off offset:48
	global_load_dwordx4 v[76:79], v[54:55], off offset:32
	global_load_dwordx4 v[98:101], v[188:189], off offset:384
	s_nop 0
	global_load_dwordx4 v[186:189], v[54:55], off offset:16
	v_add_f32_e32 v58, v68, v59
	v_pk_fma_f32 v[54:55], v[68:69], v[68:69], v[56:57]
	v_add_f32_e32 v57, v69, v58
	v_mul_f32_e32 v56, v69, v69
	v_pk_add_f32 v[54:55], v[56:57], v[54:55] op_sel_hi:[0,1]
	v_add_f32_e32 v56, v66, v57
	v_pk_fma_f32 v[54:55], v[66:67], v[66:67], v[54:55]
	v_add_f32_e32 v57, v67, v56
	v_mul_f32_e32 v56, v67, v67
	v_pk_add_f32 v[54:55], v[56:57], v[54:55] op_sel_hi:[0,1]
	s_waitcnt vmcnt(9)
	v_pk_fma_f32 v[60:61], v[234:235], s[0:1], v[34:35] op_sel_hi:[1,0,1]
	v_pk_fma_f32 v[64:65], v[236:237], s[0:1], v[36:37] op_sel_hi:[1,0,1]
	v_add_f32_e32 v56, v60, v57
	v_pk_fma_f32 v[34:35], v[60:61], v[60:61], v[54:55]
	v_add_f32_e32 v55, v61, v56
	v_mul_f32_e32 v54, v61, v61
	v_pk_add_f32 v[34:35], v[54:55], v[34:35] op_sel_hi:[0,1]
	v_add_f32_e32 v36, v64, v55
	v_pk_fma_f32 v[34:35], v[64:65], v[64:65], v[34:35]
	v_add_f32_e32 v37, v65, v36
	v_mul_f32_e32 v36, v65, v65
	s_waitcnt vmcnt(8)
	v_pk_fma_f32 v[56:57], v[238:239], s[0:1], v[38:39] op_sel_hi:[1,0,1]
	v_pk_add_f32 v[34:35], v[36:37], v[34:35] op_sel_hi:[0,1]
	v_add_f32_e32 v36, v56, v37
	v_pk_fma_f32 v[34:35], v[56:57], v[56:57], v[34:35]
	v_add_f32_e32 v37, v57, v36
	v_mul_f32_e32 v36, v57, v57
	v_pk_fma_f32 v[62:63], v[240:241], s[0:1], v[40:41] op_sel_hi:[1,0,1]
	v_pk_add_f32 v[34:35], v[36:37], v[34:35] op_sel_hi:[0,1]
	v_add_f32_e32 v36, v62, v37
	v_pk_fma_f32 v[34:35], v[62:63], v[62:63], v[34:35]
	v_add_f32_e32 v37, v63, v36
	v_mul_f32_e32 v36, v63, v63
	v_pk_fma_f32 v[54:55], v[230:231], s[0:1], v[42:43] op_sel_hi:[1,0,1]
	v_pk_add_f32 v[34:35], v[36:37], v[34:35] op_sel_hi:[0,1]
	v_add_f32_e32 v36, v54, v37
	v_pk_fma_f32 v[34:35], v[54:55], v[54:55], v[34:35]
	v_add_f32_e32 v37, v55, v36
	v_mul_f32_e32 v36, v55, v55
	v_pk_fma_f32 v[58:59], v[232:233], s[0:1], v[44:45] op_sel_hi:[1,0,1]
	v_pk_add_f32 v[34:35], v[36:37], v[34:35] op_sel_hi:[0,1]
	v_add_f32_e32 v36, v58, v37
	v_pk_fma_f32 v[34:35], v[58:59], v[58:59], v[34:35]
	v_add_f32_e32 v37, v59, v36
	v_mul_f32_e32 v36, v59, v59
	v_pk_fma_f32 v[44:45], v[82:83], s[0:1], v[46:47] op_sel_hi:[1,0,1]
	v_pk_add_f32 v[34:35], v[36:37], v[34:35] op_sel_hi:[0,1]
	v_add_f32_e32 v36, v44, v37
	v_pk_fma_f32 v[34:35], v[44:45], v[44:45], v[34:35]
	v_add_f32_e32 v37, v45, v36
	v_mul_f32_e32 v36, v45, v45
	v_pk_fma_f32 v[46:47], v[84:85], s[0:1], v[48:49] op_sel_hi:[1,0,1]
	v_pk_add_f32 v[34:35], v[36:37], v[34:35] op_sel_hi:[0,1]
	v_add_f32_e32 v36, v46, v37
	v_pk_fma_f32 v[34:35], v[46:47], v[46:47], v[34:35]
	v_add_f32_e32 v37, v47, v36
	v_mul_f32_e32 v36, v47, v47
	v_pk_add_f32 v[34:35], v[36:37], v[34:35] op_sel_hi:[0,1]
	s_waitcnt vmcnt(5)
	v_pk_fma_f32 v[38:39], v[250:251], s[0:1], v[18:19] op_sel_hi:[1,0,1]
	v_pk_fma_f32 v[42:43], v[252:253], s[0:1], v[20:21] op_sel_hi:[1,0,1]
	v_add_f32_e32 v36, v38, v37
	v_pk_fma_f32 v[18:19], v[38:39], v[38:39], v[34:35]
	v_add_f32_e32 v35, v39, v36
	v_mul_f32_e32 v34, v39, v39
	v_pk_add_f32 v[18:19], v[34:35], v[18:19] op_sel_hi:[0,1]
	v_add_f32_e32 v20, v42, v35
	v_pk_fma_f32 v[18:19], v[42:43], v[42:43], v[18:19]
	v_add_f32_e32 v21, v43, v20
	v_mul_f32_e32 v20, v43, v43
	s_waitcnt vmcnt(4)
; #define RL_LOAD(XV, G) { constexpr int mt__ = (G) >> 2, half__ = ((G) >> 1) & 1, nt__ = (G) & 1; \
;     _Pragma("unroll") for (int gq = 0; gq < 4; ++gq) XV[gq] = *(const f32x4*)(xin + rbase + (size_t)mt__ * 32 * 1024 + half__ * 64 + nt__ * 32 + 4 * gq); }
; #define RL_FOLD(XV, G, SM, SQ) { constexpr int mt__ = (G) >> 2, half__ = ((G) >> 1) & 1, nt__ = (G) & 1; \
;     _Pragma("unroll") for (int gq = 0; gq < 4; ++gq) _Pragma("unroll") for (int jj = 0; jj < 4; ++jj) { \
;       const float y = ALPHA * XV[gq][jj] + acc[half__][nt__][mt__][4 * gq + jj]; acc[half__][nt__][mt__][4 * gq + jj] = y; SM += y; SQ += y * y; } }
; #define SB __builtin_amdgcn_sched_barrier(0)
;   DI void full(const int mt_, const int nt_, f32x16 (&acc)[2][2][2], const int tw, const int fw, const int r, const int hh, char* lds, const int tid) const {
;     ...
;     float sm0 = 0.f, sq0 = 0.f, sm1 = 0.f, sq1 = 0.f;
;     RL_LOAD(xa, 0); RL_LOAD(xc, 1); RL_LOAD(xe, 2); SB;
;     RL_FOLD(xa, 0, sm0, sq0); SB; RL_LOAD(xa, 3); SB;
;     RL_FOLD(xc, 1, sm0, sq0); SB; RL_LOAD(xc, 4); SB;
;     RL_FOLD(xe, 2, sm0, sq0); SB; RL_LOAD(xe, 5); SB;
;     RL_FOLD(xa, 3, sm0, sq0); SB; RL_LOAD(xa, 6); SB;
;     RL_FOLD(xc, 4, sm1, sq1); SB; RL_LOAD(xc, 7); SB;
;     RL_FOLD(xe, 5, sm1, sq1); SB;
;     RL_FOLD(xa, 6, sm1, sq1); SB;
;     RL_FOLD(xc, 7, sm1, sq1);
;     ...
;     sm0 += __shfl_xor(sm0, 32, 64); sq0 += __shfl_xor(sq0, 32, 64); sm1 += __shfl_xor(sm1, 32, 64); sq1 += __shfl_xor(sq1, 32, 64);
;     if (hh == 0) {
;       float* pp = part + ((fw * 256) + tw * 64 + r) * 2; pp[0] = sm0; pp[1] = sq0;
;       pp[64] = sm1; pp[65] = sq1;
;     }
	v_pk_fma_f32 v[34:35], v[166:167], s[0:1], v[22:23] op_sel_hi:[1,0,1]
	v_pk_add_f32 v[18:19], v[20:21], v[18:19] op_sel_hi:[0,1]
	v_add_f32_e32 v20, v34, v21
	v_pk_fma_f32 v[18:19], v[34:35], v[34:35], v[18:19]
	v_add_f32_e32 v21, v35, v20
	v_mul_f32_e32 v20, v35, v35
	v_pk_fma_f32 v[40:41], v[168:169], s[0:1], v[24:25] op_sel_hi:[1,0,1]
	v_pk_add_f32 v[18:19], v[20:21], v[18:19] op_sel_hi:[0,1]
	v_add_f32_e32 v20, v40, v21
	v_pk_fma_f32 v[18:19], v[40:41], v[40:41], v[18:19]
	v_add_f32_e32 v21, v41, v20
	v_mul_f32_e32 v20, v41, v41
	v_pk_fma_f32 v[26:27], v[246:247], s[0:1], v[26:27] op_sel_hi:[1,0,1]
	v_pk_add_f32 v[18:19], v[20:21], v[18:19] op_sel_hi:[0,1]
	v_add_f32_e32 v20, v26, v21
	v_pk_fma_f32 v[18:19], v[26:27], v[26:27], v[18:19]
	v_add_f32_e32 v21, v27, v20
	v_mul_f32_e32 v20, v27, v27
	v_pk_fma_f32 v[36:37], v[248:249], s[0:1], v[28:29] op_sel_hi:[1,0,1]
	v_pk_add_f32 v[18:19], v[20:21], v[18:19] op_sel_hi:[0,1]
	v_add_f32_e32 v20, v36, v21
	v_pk_fma_f32 v[18:19], v[36:37], v[36:37], v[18:19]
	v_add_f32_e32 v21, v37, v20
	v_mul_f32_e32 v20, v37, v37
	v_pk_fma_f32 v[24:25], v[242:243], s[0:1], v[30:31] op_sel_hi:[1,0,1]
	v_pk_add_f32 v[18:19], v[20:21], v[18:19] op_sel_hi:[0,1]
	v_add_f32_e32 v20, v24, v21
	v_pk_fma_f32 v[18:19], v[24:25], v[24:25], v[18:19]
	v_add_f32_e32 v21, v25, v20
	v_mul_f32_e32 v20, v25, v25
	v_pk_fma_f32 v[28:29], v[244:245], s[0:1], v[32:33] op_sel_hi:[1,0,1]
	v_pk_add_f32 v[18:19], v[20:21], v[18:19] op_sel_hi:[0,1]
	v_add_f32_e32 v20, v28, v21
	v_pk_fma_f32 v[18:19], v[28:29], v[28:29], v[18:19]
	v_add_f32_e32 v22, v29, v20
	v_mul_f32_e32 v20, v29, v29
	v_pk_add_f32 v[20:21], v[20:21], v[18:19] op_sel_hi:[0,1]
	s_waitcnt vmcnt(1)
	v_pk_fma_f32 v[18:19], v[98:99], s[0:1], v[2:3] op_sel_hi:[1,0,1]
	s_waitcnt vmcnt(0)
	v_pk_fma_f32 v[6:7], v[186:187], s[0:1], v[6:7] op_sel_hi:[1,0,1]
	v_add_f32_e32 v22, v18, v22
	v_pk_fma_f32 v[2:3], v[18:19], v[18:19], v[20:21]
	v_add_f32_e32 v21, v19, v22
	v_pk_fma_f32 v[22:23], v[100:101], s[0:1], v[4:5] op_sel_hi:[1,0,1]
	v_mul_f32_e32 v20, v19, v19
	v_add_f32_e32 v4, v22, v21
	v_pk_add_f32 v[2:3], v[20:21], v[2:3] op_sel_hi:[0,1]
	v_add_f32_e32 v4, v23, v4
	v_pk_fma_f32 v[2:3], v[22:23], v[22:23], v[2:3]
	v_add_f32_e32 v21, v6, v4
	v_mul_f32_e32 v20, v23, v23
	v_mov_b32_e32 v4, v6
	v_mov_b32_e32 v5, v23
	v_pk_add_f32 v[2:3], v[20:21], v[2:3] op_sel_hi:[0,1]
	v_pk_fma_f32 v[2:3], v[4:5], v[4:5], v[2:3]
	v_add_f32_e32 v4, v7, v21
	v_pk_fma_f32 v[20:21], v[188:189], s[0:1], v[8:9] op_sel_hi:[1,0,1]
	v_mul_f32_e32 v8, v7, v7
	v_add_f32_e32 v9, v20, v4
	v_mov_b32_e32 v4, v20
	v_mov_b32_e32 v5, v7
	v_pk_add_f32 v[2:3], v[8:9], v[2:3] op_sel_hi:[0,1]
	v_pk_fma_f32 v[4:5], v[4:5], v[4:5], v[2:3]
	v_add_f32_e32 v8, v21, v9
	v_pk_fma_f32 v[2:3], v[76:77], s[0:1], v[10:11] op_sel_hi:[1,0,1]
	v_mul_f32_e32 v10, v21, v21
	v_add_f32_e32 v11, v2, v8
	v_mov_b32_e32 v8, v2
	v_mov_b32_e32 v9, v21
	v_pk_add_f32 v[4:5], v[10:11], v[4:5] op_sel_hi:[0,1]
	v_pk_fma_f32 v[4:5], v[8:9], v[8:9], v[4:5]
	v_add_f32_e32 v10, v3, v11
	v_pk_fma_f32 v[8:9], v[78:79], s[0:1], v[12:13] op_sel_hi:[1,0,1]
	v_mul_f32_e32 v12, v3, v3
	v_add_f32_e32 v13, v8, v10
	v_mov_b32_e32 v10, v8
	v_mov_b32_e32 v11, v3
	v_pk_add_f32 v[4:5], v[12:13], v[4:5] op_sel_hi:[0,1]
	v_pk_fma_f32 v[10:11], v[10:11], v[10:11], v[4:5]
	v_add_f32_e32 v12, v9, v13
	v_pk_fma_f32 v[4:5], v[50:51], s[0:1], v[14:15] op_sel_hi:[1,0,1]
	v_mul_f32_e32 v14, v9, v9
	v_add_f32_e32 v15, v4, v12
	v_mov_b32_e32 v12, v4
	v_mov_b32_e32 v13, v9
	v_pk_add_f32 v[10:11], v[14:15], v[10:11] op_sel_hi:[0,1]
	v_pk_fma_f32 v[12:13], v[12:13], v[12:13], v[10:11]
	v_pk_fma_f32 v[10:11], v[52:53], s[0:1], v[16:17] op_sel_hi:[1,0,1]
	v_mul_f32_e32 v30, v5, v5
	v_mov_b32_e32 v16, v10
	v_mov_b32_e32 v17, v5
	v_pk_add_f32 v[12:13], v[30:31], v[12:13] op_sel_hi:[0,1]
	v_pk_fma_f32 v[12:13], v[16:17], v[16:17], v[12:13]
	v_pk_mul_f32 v[16:17], v[10:11], v[10:11]
	v_add_f32_e32 v14, v5, v15
	v_mov_b32_e32 v15, v17
	v_add_f32_e32 v14, v10, v14
	v_pk_mov_b32 v[12:13], v[10:11], v[12:13] op_sel:[1,0]
	v_pk_add_f32 v[12:13], v[12:13], v[14:15]
	v_pk_mov_b32 v[14:15], v[110:111], v[74:75] op_sel:[1,0]
	v_pk_add_f32 v[14:15], v[14:15], v[114:115]
	v_mov_b32_e32 v16, v14
	v_mov_b32_e32 v17, v15
	v_mov_b32_e32 v30, v12
	v_mov_b32_e32 v31, v13
	s_nop 1
	v_permlane32_swap_b32_e32 v16, v14
	v_permlane32_swap_b32_e32 v17, v15
	v_permlane32_swap_b32_e32 v30, v12
	v_permlane32_swap_b32_e32 v31, v13
	v_cmp_eq_u32_e32 vcc, 0, v224
	s_and_saveexec_b64 s[20:21], vcc
	s_cbranch_execz .LBB0_272
	v_lshlrev_b32_e32 v32, 3, v184
	v_and_b32_e32 v32, 0xfffffef8, v32
	v_add_u32_e32 v32, 0, v32
	v_add_u32_e32 v32, 0x12000, v32
	s_waitcnt lgkmcnt(2)
	v_pk_add_f32 v[14:15], v[14:15], v[16:17]
	s_waitcnt lgkmcnt(0)
	v_pk_add_f32 v[12:13], v[12:13], v[30:31]
	ds_write2_b64 v32, v[14:15], v[12:13] offset1:32

; #define RL_LOAD(XV, G) { constexpr int mt__ = (G) >> 2, half__ = ((G) >> 1) & 1, nt__ = (G) & 1; \
;     _Pragma("unroll") for (int gq = 0; gq < 4; ++gq) XV[gq] = *(const f32x4*)(xin + rbase + (size_t)mt__ * 32 * 1024 + half__ * 64 + nt__ * 32 + 4 * gq); }
; #define RL_FOLD(XV, G, SM, SQ) { constexpr int mt__ = (G) >> 2, half__ = ((G) >> 1) & 1, nt__ = (G) & 1; \
;     _Pragma("unroll") for (int gq = 0; gq < 4; ++gq) _Pragma("unroll") for (int jj = 0; jj < 4; ++jj) { \
;       const float y = ALPHA * XV[gq][jj] + acc[half__][nt__][mt__][4 * gq + jj]; acc[half__][nt__][mt__][4 * gq + jj] = y; SM += y; SQ += y * y; } }
; #define SB __builtin_amdgcn_sched_barrier(0)
;   DI void full(const int mt_, const int nt_, f32x16 (&acc)[2][2][2], const int tw, const int fw, const int r, const int hh, char* lds, const int tid) const {
;     ...
;     float sm0 = 0.f, sq0 = 0.f, sm1 = 0.f, sq1 = 0.f;
;     RL_LOAD(xa, 0); RL_LOAD(xc, 1); RL_LOAD(xe, 2); SB;
;     RL_FOLD(xa, 0, sm0, sq0); SB; RL_LOAD(xa, 3); SB;
;     RL_FOLD(xc, 1, sm0, sq0); SB; RL_LOAD(xc, 4); SB;
;     RL_FOLD(xe, 2, sm0, sq0); SB; RL_LOAD(xe, 5); SB;
;     RL_FOLD(xa, 3, sm0, sq0); SB; RL_LOAD(xa, 6); SB;
;     RL_FOLD(xc, 4, sm1, sq1); SB; RL_LOAD(xc, 7); SB;
;     RL_FOLD(xe, 5, sm1, sq1); SB;
;     RL_FOLD(xa, 6, sm1, sq1); SB;
;     RL_FOLD(xc, 7, sm1, sq1);
.Lkexit_3:
	v_mov_b32_e32 v184, v192
	s_waitcnt vmcnt(1)
	v_ashrrev_i32_e32 v130, 1, v184
	v_and_b32_e32 v223, 0xdf, v184
	v_and_b32_e32 v182, 0xffffff80, v130
	v_or_b32_e32 v0, s4, v223
	v_ashrrev_i32_e32 v183, 31, v182
	v_bfe_u32 v224, v184, 5, 1
	v_lshl_add_u64 v[130:131], v[182:183], 2, s[16:17]
	v_lshlrev_b64 v[132:133], 12, v[0:1]
	v_lshl_add_u64 v[130:131], v[130:131], 0, v[132:133]
	v_lshlrev_b32_e32 v132, 6, v224
	v_mov_b32_e32 v133, v1
	v_lshl_add_u64 v[186:187], v[130:131], 0, v[132:133]
	global_load_dwordx4 v[130:133], v[186:187], off offset:48
	global_load_dwordx4 v[134:137], v[186:187], off offset:32
	global_load_dwordx4 v[138:141], v[186:187], off offset:16
	global_load_dwordx4 v[142:145], v[186:187], off
	global_load_dwordx4 v[226:229], v[186:187], off offset:176
	global_load_dwordx4 v[230:233], v[186:187], off offset:160
	global_load_dwordx4 v[234:237], v[186:187], off offset:144
	global_load_dwordx4 v[146:149], v[186:187], off offset:128
	global_load_dwordx4 v[238:241], v[186:187], off offset:304
	global_load_dwordx4 v[242:245], v[186:187], off offset:288
	global_load_dwordx4 v[246:249], v[186:187], off offset:272
	global_load_dwordx4 v[250:253], v[186:187], off offset:256
	s_waitcnt vmcnt(8)
	v_pk_fma_f32 v[178:179], v[142:143], s[0:1], v[114:115] op_sel_hi:[1,0,1]
	v_pk_fma_f32 v[180:181], v[144:145], s[0:1], v[116:117] op_sel_hi:[1,0,1]
	v_add_f32_e32 v114, 0, v178
	v_add_f32_e32 v142, v179, v114
	v_mul_f32_e32 v114, v179, v179
	v_pk_fma_f32 v[114:115], v[178:179], v[178:179], v[114:115] op_sel_hi:[1,1,0]
	v_add_f32_e32 v116, v180, v142
	v_pk_fma_f32 v[114:115], v[180:181], v[180:181], v[114:115]
	v_add_f32_e32 v117, v181, v116
	v_mul_f32_e32 v116, v181, v181
	v_pk_fma_f32 v[158:159], v[138:139], s[0:1], v[118:119] op_sel_hi:[1,0,1]
	v_pk_add_f32 v[114:115], v[116:117], v[114:115] op_sel_hi:[0,1]
	v_add_f32_e32 v116, v158, v117
	v_pk_fma_f32 v[114:115], v[158:159], v[158:159], v[114:115]
	v_add_f32_e32 v117, v159, v116
	v_mul_f32_e32 v116, v159, v159
	v_pk_fma_f32 v[160:161], v[140:141], s[0:1], v[120:121] op_sel_hi:[1,0,1]
	v_pk_add_f32 v[114:115], v[116:117], v[114:115] op_sel_hi:[0,1]
	v_add_f32_e32 v116, v160, v117
	v_pk_fma_f32 v[114:115], v[160:161], v[160:161], v[114:115]
	v_add_f32_e32 v117, v161, v116
	v_mul_f32_e32 v116, v161, v161
	v_pk_fma_f32 v[154:155], v[134:135], s[0:1], v[122:123] op_sel_hi:[1,0,1]
	v_pk_add_f32 v[114:115], v[116:117], v[114:115] op_sel_hi:[0,1]
	v_add_f32_e32 v116, v154, v117
	v_pk_fma_f32 v[114:115], v[154:155], v[154:155], v[114:115]
	v_add_f32_e32 v117, v155, v116
	v_mul_f32_e32 v116, v155, v155
	v_pk_fma_f32 v[156:157], v[136:137], s[0:1], v[124:125] op_sel_hi:[1,0,1]
	v_pk_add_f32 v[114:115], v[116:117], v[114:115] op_sel_hi:[0,1]
	v_add_f32_e32 v116, v156, v117
	v_pk_fma_f32 v[114:115], v[156:157], v[156:157], v[114:115]
	v_add_f32_e32 v124, v157, v116
	v_mul_f32_e32 v116, v157, v157
	v_pk_add_f32 v[114:115], v[116:117], v[114:115] op_sel_hi:[0,1]
	v_pk_fma_f32 v[152:153], v[130:131], s[0:1], v[126:127] op_sel_hi:[1,0,1]
	v_pk_fma_f32 v[150:151], v[132:133], s[0:1], v[128:129] op_sel_hi:[1,0,1]
	v_pk_fma_f32 v[114:115], v[152:153], v[152:153], v[114:115]
	v_mul_f32_e32 v116, v153, v153
	v_pk_add_f32 v[114:115], v[116:117], v[114:115] op_sel_hi:[0,1]
	v_pk_fma_f32 v[114:115], v[150:151], v[150:151], v[114:115]
	v_mul_f32_e32 v116, v151, v151
	v_pk_add_f32 v[118:119], v[116:117], v[114:115] op_sel_hi:[0,1]
	global_load_dwordx4 v[114:117], v[186:187], off offset:432
	global_load_dwordx4 v[202:205], v[186:187], off offset:416
	global_load_dwordx4 v[194:197], v[186:187], off offset:400
	global_load_dwordx4 v[120:123], v[186:187], off offset:384
	v_add_f32_e32 v124, v152, v124
	v_add_f32_e32 v124, v153, v124
	v_add_f32_e32 v124, v150, v124
	v_add_f32_e32 v124, v151, v124
	s_waitcnt vmcnt(8)
	v_pk_fma_f32 v[144:145], v[146:147], s[0:1], v[98:99] op_sel_hi:[1,0,1]
	v_pk_fma_f32 v[148:149], v[148:149], s[0:1], v[100:101] op_sel_hi:[1,0,1]
	v_add_f32_e32 v124, v144, v124
	v_pk_fma_f32 v[98:99], v[144:145], v[144:145], v[118:119]
	v_add_f32_e32 v119, v145, v124
	v_mul_f32_e32 v118, v145, v145
	v_pk_add_f32 v[98:99], v[118:119], v[98:99] op_sel_hi:[0,1]
	v_add_f32_e32 v100, v148, v119
	v_pk_fma_f32 v[98:99], v[148:149], v[148:149], v[98:99]
	v_add_f32_e32 v101, v149, v100
	v_mul_f32_e32 v100, v149, v149
	v_pk_fma_f32 v[138:139], v[234:235], s[0:1], v[102:103] op_sel_hi:[1,0,1]
	v_pk_add_f32 v[98:99], v[100:101], v[98:99] op_sel_hi:[0,1]
	v_add_f32_e32 v100, v138, v101
	v_pk_fma_f32 v[98:99], v[138:139], v[138:139], v[98:99]
	v_add_f32_e32 v101, v139, v100
	v_mul_f32_e32 v100, v139, v139
	v_pk_fma_f32 v[146:147], v[236:237], s[0:1], v[104:105] op_sel_hi:[1,0,1]
	v_pk_add_f32 v[98:99], v[100:101], v[98:99] op_sel_hi:[0,1]
	v_add_f32_e32 v100, v146, v101
	v_pk_fma_f32 v[98:99], v[146:147], v[146:147], v[98:99]
	v_add_f32_e32 v101, v147, v100
	v_mul_f32_e32 v100, v147, v147
	v_pk_fma_f32 v[130:131], v[230:231], s[0:1], v[106:107] op_sel_hi:[1,0,1]
	v_pk_add_f32 v[98:99], v[100:101], v[98:99] op_sel_hi:[0,1]
	v_add_f32_e32 v100, v130, v101
	v_pk_fma_f32 v[98:99], v[130:131], v[130:131], v[98:99]
	v_add_f32_e32 v101, v131, v100
	v_mul_f32_e32 v100, v131, v131
	v_pk_fma_f32 v[140:141], v[232:233], s[0:1], v[108:109] op_sel_hi:[1,0,1]
	v_pk_add_f32 v[98:99], v[100:101], v[98:99] op_sel_hi:[0,1]
	v_add_f32_e32 v100, v140, v101
	v_pk_fma_f32 v[98:99], v[140:141], v[140:141], v[98:99]
	v_add_f32_e32 v106, v141, v100
	v_mul_f32_e32 v100, v141, v141
	v_pk_add_f32 v[102:103], v[100:101], v[98:99] op_sel_hi:[0,1]
	v_pk_fma_f32 v[124:125], v[226:227], s[0:1], v[110:111] op_sel_hi:[1,0,1]
	v_pk_fma_f32 v[134:135], v[228:229], s[0:1], v[112:113] op_sel_hi:[1,0,1]
	v_add_co_u32_e32 v188, vcc, s91, v186
	s_mov_b64 s[18:19], 0x20000
	s_nop 0
	v_addc_co_u32_e32 v189, vcc, 0, v187, vcc
	v_lshl_add_u64 v[104:105], v[186:187], 0, s[18:19]
	global_load_dwordx4 v[226:229], v[188:189], off
	global_load_dwordx4 v[98:101], v[104:105], off offset:48
	global_load_dwordx4 v[230:233], v[104:105], off offset:32
	global_load_dwordx4 v[234:237], v[104:105], off offset:16
	v_add_f32_e32 v104, v124, v106
	v_pk_fma_f32 v[102:103], v[124:125], v[124:125], v[102:103]
	v_add_f32_e32 v105, v125, v104
	v_mul_f32_e32 v104, v125, v125
	v_pk_add_f32 v[102:103], v[104:105], v[102:103] op_sel_hi:[0,1]
	v_add_f32_e32 v104, v134, v105
	v_pk_fma_f32 v[102:103], v[134:135], v[134:135], v[102:103]
	v_add_f32_e32 v105, v135, v104
	v_mul_f32_e32 v104, v135, v135
	v_pk_add_f32 v[102:103], v[104:105], v[102:103] op_sel_hi:[0,1]
	s_waitcnt vmcnt(8)
; #define RL_LOAD(XV, G) { constexpr int mt__ = (G) >> 2, half__ = ((G) >> 1) & 1, nt__ = (G) & 1; \
;     _Pragma("unroll") for (int gq = 0; gq < 4; ++gq) XV[gq] = *(const f32x4*)(xin + rbase + (size_t)mt__ * 32 * 1024 + half__ * 64 + nt__ * 32 + 4 * gq); }
; #define RL_FOLD(XV, G, SM, SQ) { constexpr int mt__ = (G) >> 2, half__ = ((G) >> 1) & 1, nt__ = (G) & 1; \
;     _Pragma("unroll") for (int gq = 0; gq < 4; ++gq) _Pragma("unroll") for (int jj = 0; jj < 4; ++jj) { \
;       const float y = ALPHA * XV[gq][jj] + acc[half__][nt__][mt__][4 * gq + jj]; acc[half__][nt__][mt__][4 * gq + jj] = y; SM += y; SQ += y * y; } }
; #define SB __builtin_amdgcn_sched_barrier(0)
;   DI void full(const int mt_, const int nt_, f32x16 (&acc)[2][2][2], const int tw, const int fw, const int r, const int hh, char* lds, const int tid) const {
;     ...
;     float sm0 = 0.f, sq0 = 0.f, sm1 = 0.f, sq1 = 0.f;
;     RL_LOAD(xa, 0); RL_LOAD(xc, 1); RL_LOAD(xe, 2); SB;
;     RL_FOLD(xa, 0, sm0, sq0); SB; RL_LOAD(xa, 3); SB;
;     RL_FOLD(xc, 1, sm0, sq0); SB; RL_LOAD(xc, 4); SB;
;     RL_FOLD(xe, 2, sm0, sq0); SB; RL_LOAD(xe, 5); SB;
;     RL_FOLD(xa, 3, sm0, sq0); SB; RL_LOAD(xa, 6); SB;
;     RL_FOLD(xc, 4, sm1, sq1); SB; RL_LOAD(xc, 7); SB;
;     RL_FOLD(xe, 5, sm1, sq1); SB;
;     RL_FOLD(xa, 6, sm1, sq1); SB;
;     RL_FOLD(xc, 7, sm1, sq1);
	v_pk_fma_f32 v[132:133], v[250:251], s[0:1], v[82:83] op_sel_hi:[1,0,1]
	v_pk_fma_f32 v[142:143], v[252:253], s[0:1], v[84:85] op_sel_hi:[1,0,1]
	v_add_f32_e32 v104, v132, v105
	v_pk_fma_f32 v[82:83], v[132:133], v[132:133], v[102:103]
	v_add_f32_e32 v103, v133, v104
	v_mul_f32_e32 v102, v133, v133
	v_pk_add_f32 v[82:83], v[102:103], v[82:83] op_sel_hi:[0,1]
	v_add_f32_e32 v84, v142, v103
	v_pk_fma_f32 v[82:83], v[142:143], v[142:143], v[82:83]
	v_add_f32_e32 v85, v143, v84
	v_mul_f32_e32 v84, v143, v143
	v_pk_fma_f32 v[126:127], v[246:247], s[0:1], v[86:87] op_sel_hi:[1,0,1]
	v_pk_add_f32 v[82:83], v[84:85], v[82:83] op_sel_hi:[0,1]
	v_add_f32_e32 v84, v126, v85
	v_pk_fma_f32 v[82:83], v[126:127], v[126:127], v[82:83]
	v_add_f32_e32 v85, v127, v84
	v_mul_f32_e32 v84, v127, v127
	v_pk_fma_f32 v[136:137], v[248:249], s[0:1], v[88:89] op_sel_hi:[1,0,1]
	v_pk_add_f32 v[82:83], v[84:85], v[82:83] op_sel_hi:[0,1]
	v_add_f32_e32 v84, v136, v85
	v_pk_fma_f32 v[82:83], v[136:137], v[136:137], v[82:83]
	v_add_f32_e32 v85, v137, v84
	v_mul_f32_e32 v84, v137, v137
	v_pk_fma_f32 v[112:113], v[242:243], s[0:1], v[90:91] op_sel_hi:[1,0,1]
	v_pk_add_f32 v[82:83], v[84:85], v[82:83] op_sel_hi:[0,1]
	v_add_f32_e32 v84, v112, v85
	v_pk_fma_f32 v[82:83], v[112:113], v[112:113], v[82:83]
	v_add_f32_e32 v85, v113, v84
	v_mul_f32_e32 v84, v113, v113
	v_pk_fma_f32 v[128:129], v[244:245], s[0:1], v[92:93] op_sel_hi:[1,0,1]
	v_pk_add_f32 v[82:83], v[84:85], v[82:83] op_sel_hi:[0,1]
	v_add_f32_e32 v84, v128, v85
	v_pk_fma_f32 v[82:83], v[128:129], v[128:129], v[82:83]
	v_add_f32_e32 v90, v129, v84
	v_mul_f32_e32 v84, v129, v129
	v_pk_add_f32 v[86:87], v[84:85], v[82:83] op_sel_hi:[0,1]
	v_pk_fma_f32 v[106:107], v[238:239], s[0:1], v[94:95] op_sel_hi:[1,0,1]
	v_pk_fma_f32 v[118:119], v[240:241], s[0:1], v[96:97] op_sel_hi:[1,0,1]
	s_mov_b64 s[18:19], 0x20080
	v_lshl_add_u64 v[88:89], v[186:187], 0, s[18:19]
	global_load_dwordx4 v[82:85], v[88:89], off offset:48
	global_load_dwordx4 v[238:241], v[88:89], off offset:32
	global_load_dwordx4 v[242:245], v[188:189], off offset:128
	global_load_dwordx4 v[246:249], v[88:89], off offset:16
	v_add_f32_e32 v88, v106, v90
	v_pk_fma_f32 v[86:87], v[106:107], v[106:107], v[86:87]
	v_add_f32_e32 v89, v107, v88
	v_mul_f32_e32 v88, v107, v107
	v_pk_add_f32 v[86:87], v[88:89], v[86:87] op_sel_hi:[0,1]
	v_add_f32_e32 v88, v118, v89
	v_pk_fma_f32 v[86:87], v[118:119], v[118:119], v[86:87]
	v_add_f32_e32 v89, v119, v88
	v_mul_f32_e32 v88, v119, v119
	v_pk_add_f32 v[86:87], v[88:89], v[86:87] op_sel_hi:[0,1]
	s_waitcnt vmcnt(8)
	v_pk_fma_f32 v[104:105], v[120:121], s[0:1], v[50:51] op_sel_hi:[1,0,1]
	v_pk_fma_f32 v[122:123], v[122:123], s[0:1], v[52:53] op_sel_hi:[1,0,1]
	v_add_f32_e32 v88, v104, v89
	v_pk_fma_f32 v[50:51], v[104:105], v[104:105], v[86:87]
	v_add_f32_e32 v87, v105, v88
	v_mul_f32_e32 v86, v105, v105
	v_add_f32_e32 v52, v122, v87
	v_pk_add_f32 v[50:51], v[86:87], v[50:51] op_sel_hi:[0,1]
	v_add_f32_e32 v52, v123, v52
	v_pk_fma_f32 v[102:103], v[194:195], s[0:1], v[54:55] op_sel_hi:[1,0,1]
	v_pk_fma_f32 v[50:51], v[122:123], v[122:123], v[50:51]
	v_add_f32_e32 v55, v102, v52
	v_mul_f32_e32 v54, v123, v123
	v_mov_b32_e32 v52, v102
	v_mov_b32_e32 v53, v123
	v_pk_add_f32 v[50:51], v[54:55], v[50:51] op_sel_hi:[0,1]
	v_pk_fma_f32 v[50:51], v[52:53], v[52:53], v[50:51]
	v_add_f32_e32 v52, v103, v55
	v_pk_fma_f32 v[120:121], v[196:197], s[0:1], v[56:57] op_sel_hi:[1,0,1]
	v_mul_f32_e32 v54, v103, v103
	v_add_f32_e32 v55, v120, v52
	v_mov_b32_e32 v52, v120
	v_mov_b32_e32 v53, v103
	v_pk_add_f32 v[50:51], v[54:55], v[50:51] op_sel_hi:[0,1]
	v_pk_fma_f32 v[50:51], v[52:53], v[52:53], v[50:51]
	v_add_f32_e32 v52, v121, v55
	v_pk_fma_f32 v[94:95], v[202:203], s[0:1], v[58:59] op_sel_hi:[1,0,1]
	v_mul_f32_e32 v54, v121, v121
	v_add_f32_e32 v55, v94, v52
	v_mov_b32_e32 v52, v94
	v_mov_b32_e32 v53, v121
	v_pk_add_f32 v[50:51], v[54:55], v[50:51] op_sel_hi:[0,1]
	v_pk_fma_f32 v[50:51], v[52:53], v[52:53], v[50:51]
	v_add_f32_e32 v52, v95, v55
	v_pk_fma_f32 v[108:109], v[204:205], s[0:1], v[60:61] op_sel_hi:[1,0,1]
	v_mul_f32_e32 v54, v95, v95
	v_add_f32_e32 v55, v108, v52
	v_mov_b32_e32 v52, v108
	v_mov_b32_e32 v53, v95
	v_pk_add_f32 v[50:51], v[54:55], v[50:51] op_sel_hi:[0,1]
	v_pk_fma_f32 v[50:51], v[52:53], v[52:53], v[50:51]
	v_pk_fma_f32 v[96:97], v[114:115], s[0:1], v[62:63] op_sel_hi:[1,0,1]
	v_mul_f32_e32 v54, v109, v109
	v_pk_fma_f32 v[110:111], v[116:117], s[0:1], v[64:65] op_sel_hi:[1,0,1]
	v_add_f32_e32 v58, v109, v55
	v_pk_add_f32 v[50:51], v[54:55], v[50:51] op_sel_hi:[0,1]
	v_mov_b32_e32 v54, v110
	v_mov_b32_e32 v55, v97
	v_mov_b32_e32 v52, v96
	v_mov_b32_e32 v53, v109
	v_pk_mul_f32 v[114:115], v[110:111], v[110:111]
	s_mov_b64 s[18:19], 0x20100
	v_lshl_add_u64 v[56:57], v[186:187], 0, s[18:19]
	global_load_dwordx4 v[194:197], v[56:57], off offset:48
	global_load_dwordx4 v[202:205], v[56:57], off offset:32
	global_load_dwordx4 v[250:253], v[188:189], off offset:256
	global_load_dwordx4 v[166:169], v[56:57], off offset:16
	v_add_f32_e32 v56, v96, v58
	v_add_f32_e32 v56, v97, v56
	v_add_f32_e32 v114, v110, v56
	s_waitcnt vmcnt(11)
	v_pk_fma_f32 v[90:91], v[226:227], s[0:1], v[66:67] op_sel_hi:[1,0,1]
	v_pk_fma_f32 v[92:93], v[228:229], s[0:1], v[68:69] op_sel_hi:[1,0,1]
	v_add_f32_e32 v56, 0, v90
	v_add_f32_e32 v58, v91, v56
	v_mul_f32_e32 v56, v91, v91
	v_pk_fma_f32 v[56:57], v[90:91], v[90:91], v[56:57] op_sel_hi:[1,1,0]
	v_add_f32_e32 v58, v92, v58
	v_pk_fma_f32 v[56:57], v[92:93], v[92:93], v[56:57]
	v_add_f32_e32 v59, v93, v58
	v_mul_f32_e32 v58, v93, v93
	s_waitcnt vmcnt(8)
; #define RL_LOAD(XV, G) { constexpr int mt__ = (G) >> 2, half__ = ((G) >> 1) & 1, nt__ = (G) & 1; \
;     _Pragma("unroll") for (int gq = 0; gq < 4; ++gq) XV[gq] = *(const f32x4*)(xin + rbase + (size_t)mt__ * 32 * 1024 + half__ * 64 + nt__ * 32 + 4 * gq); }
; #define RL_FOLD(XV, G, SM, SQ) { constexpr int mt__ = (G) >> 2, half__ = ((G) >> 1) & 1, nt__ = (G) & 1; \
;     _Pragma("unroll") for (int gq = 0; gq < 4; ++gq) _Pragma("unroll") for (int jj = 0; jj < 4; ++jj) { \
;       const float y = ALPHA * XV[gq][jj] + acc[half__][nt__][mt__][4 * gq + jj]; acc[half__][nt__][mt__][4 * gq + jj] = y; SM += y; SQ += y * y; } }
; #define SB __builtin_amdgcn_sched_barrier(0)
;   DI void full(const int mt_, const int nt_, f32x16 (&acc)[2][2][2], const int tw, const int fw, const int r, const int hh, char* lds, const int tid) const {
;     ...
;     float sm0 = 0.f, sq0 = 0.f, sm1 = 0.f, sq1 = 0.f;
;     RL_LOAD(xa, 0); RL_LOAD(xc, 1); RL_LOAD(xe, 2); SB;
;     RL_FOLD(xa, 0, sm0, sq0); SB; RL_LOAD(xa, 3); SB;
;     RL_FOLD(xc, 1, sm0, sq0); SB; RL_LOAD(xc, 4); SB;
;     RL_FOLD(xe, 2, sm0, sq0); SB; RL_LOAD(xe, 5); SB;
;     RL_FOLD(xa, 3, sm0, sq0); SB; RL_LOAD(xa, 6); SB;
;     RL_FOLD(xc, 4, sm1, sq1); SB; RL_LOAD(xc, 7); SB;
;     RL_FOLD(xe, 5, sm1, sq1); SB;
;     RL_FOLD(xa, 6, sm1, sq1); SB;
;     RL_FOLD(xc, 7, sm1, sq1);
	v_pk_fma_f32 v[86:87], v[234:235], s[0:1], v[70:71] op_sel_hi:[1,0,1]
	v_pk_add_f32 v[56:57], v[58:59], v[56:57] op_sel_hi:[0,1]
	v_add_f32_e32 v58, v86, v59
	v_pk_fma_f32 v[56:57], v[86:87], v[86:87], v[56:57]
	v_add_f32_e32 v59, v87, v58
	v_mul_f32_e32 v58, v87, v87
	v_pk_fma_f32 v[88:89], v[236:237], s[0:1], v[72:73] op_sel_hi:[1,0,1]
	v_pk_add_f32 v[56:57], v[58:59], v[56:57] op_sel_hi:[0,1]
	v_add_f32_e32 v58, v88, v59
	v_pk_fma_f32 v[56:57], v[88:89], v[88:89], v[56:57]
	v_add_f32_e32 v59, v89, v58
	v_mul_f32_e32 v58, v89, v89
	v_pk_fma_f32 v[70:71], v[230:231], s[0:1], v[74:75] op_sel_hi:[1,0,1]
	v_pk_add_f32 v[56:57], v[58:59], v[56:57] op_sel_hi:[0,1]
	v_add_f32_e32 v58, v70, v59
	v_pk_fma_f32 v[56:57], v[70:71], v[70:71], v[56:57]
	v_add_f32_e32 v59, v71, v58
	v_mul_f32_e32 v58, v71, v71
	v_pk_fma_f32 v[72:73], v[232:233], s[0:1], v[76:77] op_sel_hi:[1,0,1]
	v_pk_add_f32 v[56:57], v[58:59], v[56:57] op_sel_hi:[0,1]
	v_add_f32_e32 v58, v72, v59
	v_pk_fma_f32 v[56:57], v[72:73], v[72:73], v[56:57]
	v_add_f32_e32 v59, v73, v58
	v_mul_f32_e32 v58, v73, v73
	v_pk_fma_f32 v[50:51], v[52:53], v[52:53], v[50:51]
	v_mul_f32_e32 v52, v97, v97
	v_pk_add_f32 v[56:57], v[58:59], v[56:57] op_sel_hi:[0,1]
	v_pk_fma_f32 v[68:69], v[98:99], s[0:1], v[78:79] op_sel_hi:[1,0,1]
	v_pk_fma_f32 v[66:67], v[100:101], s[0:1], v[80:81] op_sel_hi:[1,0,1]
	v_pk_add_f32 v[50:51], v[52:53], v[50:51] op_sel_hi:[0,1]
	v_pk_fma_f32 v[74:75], v[54:55], v[54:55], v[50:51]
	s_mov_b64 s[18:19], 0x20180
	v_lshl_add_u64 v[54:55], v[186:187], 0, s[18:19]
	global_load_dwordx4 v[50:53], v[54:55], off offset:48
	global_load_dwordx4 v[76:79], v[54:55], off offset:32
	global_load_dwordx4 v[98:101], v[188:189], off offset:384
	s_nop 0
	global_load_dwordx4 v[186:189], v[54:55], off offset:16
	v_add_f32_e32 v58, v68, v59
	v_pk_fma_f32 v[54:55], v[68:69], v[68:69], v[56:57]
	v_add_f32_e32 v57, v69, v58
	v_mul_f32_e32 v56, v69, v69
	v_pk_add_f32 v[54:55], v[56:57], v[54:55] op_sel_hi:[0,1]
	v_add_f32_e32 v56, v66, v57
	v_pk_fma_f32 v[54:55], v[66:67], v[66:67], v[54:55]
	v_add_f32_e32 v57, v67, v56
	v_mul_f32_e32 v56, v67, v67
	v_pk_add_f32 v[54:55], v[56:57], v[54:55] op_sel_hi:[0,1]
	s_waitcnt vmcnt(9)
	v_pk_fma_f32 v[60:61], v[242:243], s[0:1], v[34:35] op_sel_hi:[1,0,1]
	v_pk_fma_f32 v[64:65], v[244:245], s[0:1], v[36:37] op_sel_hi:[1,0,1]
	v_add_f32_e32 v56, v60, v57
	v_pk_fma_f32 v[34:35], v[60:61], v[60:61], v[54:55]
	v_add_f32_e32 v55, v61, v56
	v_mul_f32_e32 v54, v61, v61
	v_pk_add_f32 v[34:35], v[54:55], v[34:35] op_sel_hi:[0,1]
	v_add_f32_e32 v36, v64, v55
	v_pk_fma_f32 v[34:35], v[64:65], v[64:65], v[34:35]
	v_add_f32_e32 v37, v65, v36
	v_mul_f32_e32 v36, v65, v65
	s_waitcnt vmcnt(8)
	v_pk_fma_f32 v[56:57], v[246:247], s[0:1], v[38:39] op_sel_hi:[1,0,1]
	v_pk_add_f32 v[34:35], v[36:37], v[34:35] op_sel_hi:[0,1]
	v_add_f32_e32 v36, v56, v37
	v_pk_fma_f32 v[34:35], v[56:57], v[56:57], v[34:35]
	v_add_f32_e32 v37, v57, v36
	v_mul_f32_e32 v36, v57, v57
	v_pk_fma_f32 v[62:63], v[248:249], s[0:1], v[40:41] op_sel_hi:[1,0,1]
	v_pk_add_f32 v[34:35], v[36:37], v[34:35] op_sel_hi:[0,1]
	v_add_f32_e32 v36, v62, v37
	v_pk_fma_f32 v[34:35], v[62:63], v[62:63], v[34:35]
	v_add_f32_e32 v37, v63, v36
	v_mul_f32_e32 v36, v63, v63
	v_pk_fma_f32 v[54:55], v[238:239], s[0:1], v[42:43] op_sel_hi:[1,0,1]
	v_pk_add_f32 v[34:35], v[36:37], v[34:35] op_sel_hi:[0,1]
	v_add_f32_e32 v36, v54, v37
	v_pk_fma_f32 v[34:35], v[54:55], v[54:55], v[34:35]
	v_add_f32_e32 v37, v55, v36
	v_mul_f32_e32 v36, v55, v55
	v_pk_fma_f32 v[58:59], v[240:241], s[0:1], v[44:45] op_sel_hi:[1,0,1]
	v_pk_add_f32 v[34:35], v[36:37], v[34:35] op_sel_hi:[0,1]
	v_add_f32_e32 v36, v58, v37
	v_pk_fma_f32 v[34:35], v[58:59], v[58:59], v[34:35]
	v_add_f32_e32 v37, v59, v36
	v_mul_f32_e32 v36, v59, v59
	v_pk_fma_f32 v[44:45], v[82:83], s[0:1], v[46:47] op_sel_hi:[1,0,1]
	v_pk_add_f32 v[34:35], v[36:37], v[34:35] op_sel_hi:[0,1]
	v_add_f32_e32 v36, v44, v37
	v_pk_fma_f32 v[34:35], v[44:45], v[44:45], v[34:35]
	v_add_f32_e32 v37, v45, v36
	v_mul_f32_e32 v36, v45, v45
	v_pk_fma_f32 v[46:47], v[84:85], s[0:1], v[48:49] op_sel_hi:[1,0,1]
	v_pk_add_f32 v[34:35], v[36:37], v[34:35] op_sel_hi:[0,1]
	v_add_f32_e32 v36, v46, v37
	v_pk_fma_f32 v[34:35], v[46:47], v[46:47], v[34:35]
	v_add_f32_e32 v37, v47, v36
	v_mul_f32_e32 v36, v47, v47
	v_pk_add_f32 v[34:35], v[36:37], v[34:35] op_sel_hi:[0,1]
	s_waitcnt vmcnt(5)
	v_pk_fma_f32 v[38:39], v[250:251], s[0:1], v[18:19] op_sel_hi:[1,0,1]
	v_pk_fma_f32 v[42:43], v[252:253], s[0:1], v[20:21] op_sel_hi:[1,0,1]
	v_add_f32_e32 v36, v38, v37
	v_pk_fma_f32 v[18:19], v[38:39], v[38:39], v[34:35]
	v_add_f32_e32 v35, v39, v36
	v_mul_f32_e32 v34, v39, v39
	v_pk_add_f32 v[18:19], v[34:35], v[18:19] op_sel_hi:[0,1]
	v_add_f32_e32 v20, v42, v35
	v_pk_fma_f32 v[18:19], v[42:43], v[42:43], v[18:19]
	v_add_f32_e32 v21, v43, v20
	v_mul_f32_e32 v20, v43, v43
	s_waitcnt vmcnt(4)
; #define RL_LOAD(XV, G) { constexpr int mt__ = (G) >> 2, half__ = ((G) >> 1) & 1, nt__ = (G) & 1; \
;     _Pragma("unroll") for (int gq = 0; gq < 4; ++gq) XV[gq] = *(const f32x4*)(xin + rbase + (size_t)mt__ * 32 * 1024 + half__ * 64 + nt__ * 32 + 4 * gq); }
; #define RL_FOLD(XV, G, SM, SQ) { constexpr int mt__ = (G) >> 2, half__ = ((G) >> 1) & 1, nt__ = (G) & 1; \
;     _Pragma("unroll") for (int gq = 0; gq < 4; ++gq) _Pragma("unroll") for (int jj = 0; jj < 4; ++jj) { \
;       const float y = ALPHA * XV[gq][jj] + acc[half__][nt__][mt__][4 * gq + jj]; acc[half__][nt__][mt__][4 * gq + jj] = y; SM += y; SQ += y * y; } }
; #define SB __builtin_amdgcn_sched_barrier(0)
;   DI void full(const int mt_, const int nt_, f32x16 (&acc)[2][2][2], const int tw, const int fw, const int r, const int hh, char* lds, const int tid) const {
;     ...
;     float sm0 = 0.f, sq0 = 0.f, sm1 = 0.f, sq1 = 0.f;
;     RL_LOAD(xa, 0); RL_LOAD(xc, 1); RL_LOAD(xe, 2); SB;
;     RL_FOLD(xa, 0, sm0, sq0); SB; RL_LOAD(xa, 3); SB;
;     RL_FOLD(xc, 1, sm0, sq0); SB; RL_LOAD(xc, 4); SB;
;     RL_FOLD(xe, 2, sm0, sq0); SB; RL_LOAD(xe, 5); SB;
;     RL_FOLD(xa, 3, sm0, sq0); SB; RL_LOAD(xa, 6); SB;
;     RL_FOLD(xc, 4, sm1, sq1); SB; RL_LOAD(xc, 7); SB;
;     RL_FOLD(xe, 5, sm1, sq1); SB;
;     RL_FOLD(xa, 6, sm1, sq1); SB;
;     RL_FOLD(xc, 7, sm1, sq1);
;     ...
;     sm0 += __shfl_xor(sm0, 32, 64); sq0 += __shfl_xor(sq0, 32, 64); sm1 += __shfl_xor(sm1, 32, 64); sq1 += __shfl_xor(sq1, 32, 64);
;     if (hh == 0) {
;       float* pp = part + ((fw * 256) + tw * 64 + r) * 2; pp[0] = sm0; pp[1] = sq0;
;       pp[64] = sm1; pp[65] = sq1;
	v_pk_fma_f32 v[34:35], v[166:167], s[0:1], v[22:23] op_sel_hi:[1,0,1]
	v_pk_add_f32 v[18:19], v[20:21], v[18:19] op_sel_hi:[0,1]
	v_add_f32_e32 v20, v34, v21
	v_pk_fma_f32 v[18:19], v[34:35], v[34:35], v[18:19]
	v_add_f32_e32 v21, v35, v20
	v_mul_f32_e32 v20, v35, v35
	v_pk_fma_f32 v[40:41], v[168:169], s[0:1], v[24:25] op_sel_hi:[1,0,1]
	v_pk_add_f32 v[18:19], v[20:21], v[18:19] op_sel_hi:[0,1]
	v_add_f32_e32 v20, v40, v21
	v_pk_fma_f32 v[18:19], v[40:41], v[40:41], v[18:19]
	v_add_f32_e32 v21, v41, v20
	v_mul_f32_e32 v20, v41, v41
	v_pk_fma_f32 v[26:27], v[202:203], s[0:1], v[26:27] op_sel_hi:[1,0,1]
	v_pk_add_f32 v[18:19], v[20:21], v[18:19] op_sel_hi:[0,1]
	v_add_f32_e32 v20, v26, v21
	v_pk_fma_f32 v[18:19], v[26:27], v[26:27], v[18:19]
	v_add_f32_e32 v21, v27, v20
	v_mul_f32_e32 v20, v27, v27
	v_pk_fma_f32 v[36:37], v[204:205], s[0:1], v[28:29] op_sel_hi:[1,0,1]
	v_pk_add_f32 v[18:19], v[20:21], v[18:19] op_sel_hi:[0,1]
	v_add_f32_e32 v20, v36, v21
	v_pk_fma_f32 v[18:19], v[36:37], v[36:37], v[18:19]
	v_add_f32_e32 v21, v37, v20
	v_mul_f32_e32 v20, v37, v37
	v_pk_fma_f32 v[24:25], v[194:195], s[0:1], v[30:31] op_sel_hi:[1,0,1]
	v_pk_add_f32 v[18:19], v[20:21], v[18:19] op_sel_hi:[0,1]
	v_add_f32_e32 v20, v24, v21
	v_pk_fma_f32 v[18:19], v[24:25], v[24:25], v[18:19]
	v_add_f32_e32 v21, v25, v20
	v_mul_f32_e32 v20, v25, v25
	v_pk_fma_f32 v[28:29], v[196:197], s[0:1], v[32:33] op_sel_hi:[1,0,1]
	v_pk_add_f32 v[18:19], v[20:21], v[18:19] op_sel_hi:[0,1]
	v_add_f32_e32 v20, v28, v21
	v_pk_fma_f32 v[18:19], v[28:29], v[28:29], v[18:19]
	v_add_f32_e32 v22, v29, v20
	v_mul_f32_e32 v20, v29, v29
	v_pk_add_f32 v[20:21], v[20:21], v[18:19] op_sel_hi:[0,1]
	s_waitcnt vmcnt(1)
	v_pk_fma_f32 v[18:19], v[98:99], s[0:1], v[2:3] op_sel_hi:[1,0,1]
	s_waitcnt vmcnt(0)
	v_pk_fma_f32 v[6:7], v[186:187], s[0:1], v[6:7] op_sel_hi:[1,0,1]
	v_add_f32_e32 v22, v18, v22
	v_pk_fma_f32 v[2:3], v[18:19], v[18:19], v[20:21]
	v_add_f32_e32 v21, v19, v22
	v_pk_fma_f32 v[22:23], v[100:101], s[0:1], v[4:5] op_sel_hi:[1,0,1]
	v_mul_f32_e32 v20, v19, v19
	v_add_f32_e32 v4, v22, v21
	v_pk_add_f32 v[2:3], v[20:21], v[2:3] op_sel_hi:[0,1]
	v_add_f32_e32 v4, v23, v4
	v_pk_fma_f32 v[2:3], v[22:23], v[22:23], v[2:3]
	v_add_f32_e32 v21, v6, v4
	v_mul_f32_e32 v20, v23, v23
	v_mov_b32_e32 v4, v6
	v_mov_b32_e32 v5, v23
	v_pk_add_f32 v[2:3], v[20:21], v[2:3] op_sel_hi:[0,1]
	v_pk_fma_f32 v[2:3], v[4:5], v[4:5], v[2:3]
	v_add_f32_e32 v4, v7, v21
	v_pk_fma_f32 v[20:21], v[188:189], s[0:1], v[8:9] op_sel_hi:[1,0,1]
	v_mul_f32_e32 v8, v7, v7
	v_add_f32_e32 v9, v20, v4
	v_mov_b32_e32 v4, v20
	v_mov_b32_e32 v5, v7
	v_pk_add_f32 v[2:3], v[8:9], v[2:3] op_sel_hi:[0,1]
	v_pk_fma_f32 v[4:5], v[4:5], v[4:5], v[2:3]
	v_add_f32_e32 v8, v21, v9
	v_pk_fma_f32 v[2:3], v[76:77], s[0:1], v[10:11] op_sel_hi:[1,0,1]
	v_mul_f32_e32 v10, v21, v21
	v_add_f32_e32 v11, v2, v8
	v_mov_b32_e32 v8, v2
	v_mov_b32_e32 v9, v21
	v_pk_add_f32 v[4:5], v[10:11], v[4:5] op_sel_hi:[0,1]
	v_pk_fma_f32 v[4:5], v[8:9], v[8:9], v[4:5]
	v_add_f32_e32 v10, v3, v11
	v_pk_fma_f32 v[8:9], v[78:79], s[0:1], v[12:13] op_sel_hi:[1,0,1]
	v_mul_f32_e32 v12, v3, v3
	v_add_f32_e32 v13, v8, v10
	v_mov_b32_e32 v10, v8
	v_mov_b32_e32 v11, v3
	v_pk_add_f32 v[4:5], v[12:13], v[4:5] op_sel_hi:[0,1]
	v_pk_fma_f32 v[10:11], v[10:11], v[10:11], v[4:5]
	v_add_f32_e32 v12, v9, v13
	v_pk_fma_f32 v[4:5], v[50:51], s[0:1], v[14:15] op_sel_hi:[1,0,1]
	v_mul_f32_e32 v14, v9, v9
	v_add_f32_e32 v15, v4, v12
	v_mov_b32_e32 v12, v4
	v_mov_b32_e32 v13, v9
	v_pk_add_f32 v[10:11], v[14:15], v[10:11] op_sel_hi:[0,1]
	v_pk_fma_f32 v[12:13], v[12:13], v[12:13], v[10:11]
	v_pk_fma_f32 v[10:11], v[52:53], s[0:1], v[16:17] op_sel_hi:[1,0,1]
	v_mul_f32_e32 v30, v5, v5
	v_mov_b32_e32 v16, v10
	v_mov_b32_e32 v17, v5
	v_pk_add_f32 v[12:13], v[30:31], v[12:13] op_sel_hi:[0,1]
	v_pk_fma_f32 v[12:13], v[16:17], v[16:17], v[12:13]
	v_pk_mul_f32 v[16:17], v[10:11], v[10:11]
	v_add_f32_e32 v14, v5, v15
	v_mov_b32_e32 v15, v17
	v_add_f32_e32 v14, v10, v14
	v_pk_mov_b32 v[12:13], v[10:11], v[12:13] op_sel:[1,0]
	v_pk_add_f32 v[12:13], v[12:13], v[14:15]
	v_pk_mov_b32 v[14:15], v[110:111], v[74:75] op_sel:[1,0]
	v_pk_add_f32 v[14:15], v[14:15], v[114:115]
	v_mov_b32_e32 v16, v14
	v_mov_b32_e32 v17, v15
	v_mov_b32_e32 v30, v12
	v_mov_b32_e32 v31, v13
	s_nop 1
	v_permlane32_swap_b32_e32 v16, v14
	v_permlane32_swap_b32_e32 v17, v15
	v_permlane32_swap_b32_e32 v30, v12
	v_permlane32_swap_b32_e32 v31, v13
	v_cmp_eq_u32_e32 vcc, 0, v224
	s_and_saveexec_b64 s[18:19], vcc
	s_cbranch_execz .LBB0_704
	v_lshlrev_b32_e32 v32, 3, v184
	v_and_b32_e32 v32, 0xfffffef8, v32
	v_add_u32_e32 v32, 0, v32
	v_add_u32_e32 v32, 0x12000, v32
	s_waitcnt lgkmcnt(2)
	v_pk_add_f32 v[14:15], v[14:15], v[16:17]
	s_waitcnt lgkmcnt(0)
	v_pk_add_f32 v[12:13], v[12:13], v[30:31]
	ds_write2_b64 v32, v[14:15], v[12:13] offset1:32

; #define RL_LOAD(XV, G) { constexpr int mt__ = (G) >> 2, half__ = ((G) >> 1) & 1, nt__ = (G) & 1; \
;     _Pragma("unroll") for (int gq = 0; gq < 4; ++gq) XV[gq] = *(const f32x4*)(xin + rbase + (size_t)mt__ * 32 * 1024 + half__ * 64 + nt__ * 32 + 4 * gq); }
; #define RL_FOLD(XV, G, SM, SQ) { constexpr int mt__ = (G) >> 2, half__ = ((G) >> 1) & 1, nt__ = (G) & 1; \
;     _Pragma("unroll") for (int gq = 0; gq < 4; ++gq) _Pragma("unroll") for (int jj = 0; jj < 4; ++jj) { \
;       const float y = ALPHA * XV[gq][jj] + acc[half__][nt__][mt__][4 * gq + jj]; acc[half__][nt__][mt__][4 * gq + jj] = y; SM += y; SQ += y * y; } }
; #define SB __builtin_amdgcn_sched_barrier(0)
;   DI void full(const int mt_, const int nt_, f32x16 (&acc)[2][2][2], const int tw, const int fw, const int r, const int hh, char* lds, const int tid) const {
;     ...
;     const size_t rbase = (size_t)(mt_ * 256 + tw * 64 + r) * 1024 + nt_ * 256 + fw * 128 + 16 * hh;
;     f32x4 xa[4], xc[4], xe[4];
;     ...
;     float sm0 = 0.f, sq0 = 0.f, sm1 = 0.f, sq1 = 0.f;
;     RL_LOAD(xa, 0); RL_LOAD(xc, 1); RL_LOAD(xe, 2); SB;
;     RL_FOLD(xa, 0, sm0, sq0); SB; RL_LOAD(xa, 3); SB;
;     RL_FOLD(xc, 1, sm0, sq0); SB; RL_LOAD(xc, 4); SB;
;     RL_FOLD(xe, 2, sm0, sq0); SB; RL_LOAD(xe, 5); SB;
.Lkexit_5:
	v_mov_b32_e32 v186, v192
	s_waitcnt vmcnt(1)
	v_ashrrev_i32_e32 v130, 1, v186
	v_and_b32_e32 v225, 0xdf, v186
	v_and_b32_e32 v184, 0xffffff80, v130
	v_or_b32_e32 v0, s2, v225
	v_ashrrev_i32_e32 v185, 31, v184
	v_bfe_u32 v226, v186, 5, 1
	v_lshl_add_u64 v[130:131], v[184:185], 2, s[16:17]
	v_lshlrev_b64 v[132:133], 12, v[0:1]
	v_lshl_add_u64 v[130:131], v[130:131], 0, v[132:133]
	v_lshlrev_b32_e32 v132, 6, v226
	v_mov_b32_e32 v133, v1
	v_lshl_add_u64 v[188:189], v[130:131], 0, v[132:133]
	global_load_dwordx4 v[130:133], v[188:189], off offset:48
	global_load_dwordx4 v[134:137], v[188:189], off offset:32
	global_load_dwordx4 v[138:141], v[188:189], off offset:16
	global_load_dwordx4 v[142:145], v[188:189], off
	global_load_dwordx4 v[194:197], v[188:189], off offset:176
	global_load_dwordx4 v[202:205], v[188:189], off offset:160
	global_load_dwordx4 v[228:231], v[188:189], off offset:144
	global_load_dwordx4 v[146:149], v[188:189], off offset:128
	global_load_dwordx4 v[232:235], v[188:189], off offset:304
	global_load_dwordx4 v[236:239], v[188:189], off offset:288
	global_load_dwordx4 v[240:243], v[188:189], off offset:272
	global_load_dwordx4 v[244:247], v[188:189], off offset:256
	s_waitcnt vmcnt(8)
	v_pk_fma_f32 v[180:181], v[142:143], s[0:1], v[114:115] op_sel_hi:[1,0,1]
	v_pk_fma_f32 v[182:183], v[144:145], s[0:1], v[116:117] op_sel_hi:[1,0,1]
	v_add_f32_e32 v114, 0, v180
	v_add_f32_e32 v142, v181, v114
	v_mul_f32_e32 v114, v181, v181
	v_pk_fma_f32 v[114:115], v[180:181], v[180:181], v[114:115] op_sel_hi:[1,1,0]
	v_add_f32_e32 v116, v182, v142
	v_pk_fma_f32 v[114:115], v[182:183], v[182:183], v[114:115]
	v_add_f32_e32 v117, v183, v116
	v_mul_f32_e32 v116, v183, v183
	v_pk_fma_f32 v[160:161], v[138:139], s[0:1], v[118:119] op_sel_hi:[1,0,1]
	v_pk_add_f32 v[114:115], v[116:117], v[114:115] op_sel_hi:[0,1]
	v_add_f32_e32 v116, v160, v117
	v_pk_fma_f32 v[114:115], v[160:161], v[160:161], v[114:115]
	v_add_f32_e32 v117, v161, v116
	v_mul_f32_e32 v116, v161, v161
	v_pk_fma_f32 v[178:179], v[140:141], s[0:1], v[120:121] op_sel_hi:[1,0,1]
	v_pk_add_f32 v[114:115], v[116:117], v[114:115] op_sel_hi:[0,1]
	v_add_f32_e32 v116, v178, v117
	v_pk_fma_f32 v[114:115], v[178:179], v[178:179], v[114:115]
	v_add_f32_e32 v117, v179, v116
	v_mul_f32_e32 v116, v179, v179
	v_pk_fma_f32 v[156:157], v[134:135], s[0:1], v[122:123] op_sel_hi:[1,0,1]
	v_pk_add_f32 v[114:115], v[116:117], v[114:115] op_sel_hi:[0,1]
	v_add_f32_e32 v116, v156, v117
	v_pk_fma_f32 v[114:115], v[156:157], v[156:157], v[114:115]
	v_add_f32_e32 v117, v157, v116
	v_mul_f32_e32 v116, v157, v157
	v_pk_fma_f32 v[158:159], v[136:137], s[0:1], v[124:125] op_sel_hi:[1,0,1]
	v_pk_add_f32 v[114:115], v[116:117], v[114:115] op_sel_hi:[0,1]
	v_add_f32_e32 v116, v158, v117
	v_pk_fma_f32 v[114:115], v[158:159], v[158:159], v[114:115]
	v_add_f32_e32 v120, v159, v116
	v_mul_f32_e32 v116, v159, v159
	v_pk_add_f32 v[114:115], v[116:117], v[114:115] op_sel_hi:[0,1]
	v_pk_fma_f32 v[154:155], v[130:131], s[0:1], v[126:127] op_sel_hi:[1,0,1]
	v_pk_fma_f32 v[152:153], v[132:133], s[0:1], v[128:129] op_sel_hi:[1,0,1]
	v_pk_fma_f32 v[114:115], v[154:155], v[154:155], v[114:115]
	v_mul_f32_e32 v116, v155, v155
	v_pk_add_f32 v[114:115], v[116:117], v[114:115] op_sel_hi:[0,1]
	v_pk_fma_f32 v[114:115], v[152:153], v[152:153], v[114:115]
	v_mul_f32_e32 v116, v153, v153
	v_pk_add_f32 v[118:119], v[116:117], v[114:115] op_sel_hi:[0,1]
	global_load_dwordx4 v[114:117], v[188:189], off offset:432
	global_load_dwordx4 v[248:251], v[188:189], off offset:416
	global_load_dwordx4 v[166:169], v[188:189], off offset:400
	global_load_dwordx4 v[122:125], v[188:189], off offset:384
	v_add_f32_e32 v120, v154, v120
	v_add_f32_e32 v120, v155, v120
	v_add_f32_e32 v120, v152, v120
	v_add_f32_e32 v120, v153, v120
	s_waitcnt vmcnt(8)
	v_pk_fma_f32 v[146:147], v[146:147], s[0:1], v[98:99] op_sel_hi:[1,0,1]
	v_pk_fma_f32 v[150:151], v[148:149], s[0:1], v[100:101] op_sel_hi:[1,0,1]
	v_add_f32_e32 v120, v146, v120
	v_pk_fma_f32 v[98:99], v[146:147], v[146:147], v[118:119]
	v_add_f32_e32 v119, v147, v120
	v_mul_f32_e32 v118, v147, v147
	v_pk_add_f32 v[98:99], v[118:119], v[98:99] op_sel_hi:[0,1]
	v_add_f32_e32 v100, v150, v119
	v_pk_fma_f32 v[98:99], v[150:151], v[150:151], v[98:99]
	v_add_f32_e32 v101, v151, v100
	v_mul_f32_e32 v100, v151, v151
	v_pk_fma_f32 v[140:141], v[228:229], s[0:1], v[102:103] op_sel_hi:[1,0,1]
	v_pk_add_f32 v[98:99], v[100:101], v[98:99] op_sel_hi:[0,1]
	v_add_f32_e32 v100, v140, v101
	v_pk_fma_f32 v[98:99], v[140:141], v[140:141], v[98:99]
	v_add_f32_e32 v101, v141, v100
	v_mul_f32_e32 v100, v141, v141
	v_pk_fma_f32 v[148:149], v[230:231], s[0:1], v[104:105] op_sel_hi:[1,0,1]
	v_pk_add_f32 v[98:99], v[100:101], v[98:99] op_sel_hi:[0,1]
	v_add_f32_e32 v100, v148, v101
	v_pk_fma_f32 v[98:99], v[148:149], v[148:149], v[98:99]
	v_add_f32_e32 v101, v149, v100
	v_mul_f32_e32 v100, v149, v149
	v_pk_fma_f32 v[132:133], v[202:203], s[0:1], v[106:107] op_sel_hi:[1,0,1]
	v_pk_add_f32 v[98:99], v[100:101], v[98:99] op_sel_hi:[0,1]
	v_add_f32_e32 v100, v132, v101
	v_pk_fma_f32 v[98:99], v[132:133], v[132:133], v[98:99]
	v_add_f32_e32 v101, v133, v100
	v_mul_f32_e32 v100, v133, v133
	v_pk_fma_f32 v[142:143], v[204:205], s[0:1], v[108:109] op_sel_hi:[1,0,1]
	v_pk_add_f32 v[98:99], v[100:101], v[98:99] op_sel_hi:[0,1]
	v_add_f32_e32 v100, v142, v101
	v_pk_fma_f32 v[98:99], v[142:143], v[142:143], v[98:99]
	v_add_f32_e32 v106, v143, v100
	v_mul_f32_e32 v100, v143, v143
	v_pk_add_f32 v[102:103], v[100:101], v[98:99] op_sel_hi:[0,1]
	v_pk_fma_f32 v[126:127], v[194:195], s[0:1], v[110:111] op_sel_hi:[1,0,1]
	v_pk_fma_f32 v[136:137], v[196:197], s[0:1], v[112:113] op_sel_hi:[1,0,1]
	v_add_co_u32_e32 v190, vcc, s91, v188
	s_mov_b64 s[4:5], 0x20000
	s_nop 0
	v_addc_co_u32_e32 v191, vcc, 0, v189, vcc
	v_lshl_add_u64 v[104:105], v[188:189], 0, s[4:5]
	global_load_dwordx4 v[194:197], v[190:191], off
	global_load_dwordx4 v[98:101], v[104:105], off offset:48
	global_load_dwordx4 v[202:205], v[104:105], off offset:32
	global_load_dwordx4 v[228:231], v[104:105], off offset:16
	v_add_f32_e32 v104, v126, v106
	v_pk_fma_f32 v[102:103], v[126:127], v[126:127], v[102:103]
	v_add_f32_e32 v105, v127, v104
	v_mul_f32_e32 v104, v127, v127
	v_pk_add_f32 v[102:103], v[104:105], v[102:103] op_sel_hi:[0,1]
	v_add_f32_e32 v104, v136, v105
	v_pk_fma_f32 v[102:103], v[136:137], v[136:137], v[102:103]
	v_add_f32_e32 v105, v137, v104
	v_mul_f32_e32 v104, v137, v137
	v_pk_add_f32 v[102:103], v[104:105], v[102:103] op_sel_hi:[0,1]
	s_waitcnt vmcnt(8)
; #define RL_LOAD(XV, G) { constexpr int mt__ = (G) >> 2, half__ = ((G) >> 1) & 1, nt__ = (G) & 1; \
;     _Pragma("unroll") for (int gq = 0; gq < 4; ++gq) XV[gq] = *(const f32x4*)(xin + rbase + (size_t)mt__ * 32 * 1024 + half__ * 64 + nt__ * 32 + 4 * gq); }
; #define RL_FOLD(XV, G, SM, SQ) { constexpr int mt__ = (G) >> 2, half__ = ((G) >> 1) & 1, nt__ = (G) & 1; \
;     _Pragma("unroll") for (int gq = 0; gq < 4; ++gq) _Pragma("unroll") for (int jj = 0; jj < 4; ++jj) { \
;       const float y = ALPHA * XV[gq][jj] + acc[half__][nt__][mt__][4 * gq + jj]; acc[half__][nt__][mt__][4 * gq + jj] = y; SM += y; SQ += y * y; } }
; #define SB __builtin_amdgcn_sched_barrier(0)
;   DI void full(const int mt_, const int nt_, f32x16 (&acc)[2][2][2], const int tw, const int fw, const int r, const int hh, char* lds, const int tid) const {
;     ...
;     RL_FOLD(xa, 0, sm0, sq0); SB; RL_LOAD(xa, 3); SB;
;     RL_FOLD(xc, 1, sm0, sq0); SB; RL_LOAD(xc, 4); SB;
;     RL_FOLD(xe, 2, sm0, sq0); SB; RL_LOAD(xe, 5); SB;
;     RL_FOLD(xa, 3, sm0, sq0); SB; RL_LOAD(xa, 6); SB;
;     RL_FOLD(xc, 4, sm1, sq1); SB; RL_LOAD(xc, 7); SB;
;     RL_FOLD(xe, 5, sm1, sq1); SB;
;     RL_FOLD(xa, 6, sm1, sq1); SB;
	v_pk_fma_f32 v[134:135], v[244:245], s[0:1], v[82:83] op_sel_hi:[1,0,1]
	v_pk_fma_f32 v[144:145], v[246:247], s[0:1], v[84:85] op_sel_hi:[1,0,1]
	v_add_f32_e32 v104, v134, v105
	v_pk_fma_f32 v[82:83], v[134:135], v[134:135], v[102:103]
	v_add_f32_e32 v103, v135, v104
	v_mul_f32_e32 v102, v135, v135
	v_pk_add_f32 v[82:83], v[102:103], v[82:83] op_sel_hi:[0,1]
	v_add_f32_e32 v84, v144, v103
	v_pk_fma_f32 v[82:83], v[144:145], v[144:145], v[82:83]
	v_add_f32_e32 v85, v145, v84
	v_mul_f32_e32 v84, v145, v145
	v_pk_fma_f32 v[128:129], v[240:241], s[0:1], v[86:87] op_sel_hi:[1,0,1]
	v_pk_add_f32 v[82:83], v[84:85], v[82:83] op_sel_hi:[0,1]
	v_add_f32_e32 v84, v128, v85
	v_pk_fma_f32 v[82:83], v[128:129], v[128:129], v[82:83]
	v_add_f32_e32 v85, v129, v84
	v_mul_f32_e32 v84, v129, v129
	v_pk_fma_f32 v[138:139], v[242:243], s[0:1], v[88:89] op_sel_hi:[1,0,1]
	v_pk_add_f32 v[82:83], v[84:85], v[82:83] op_sel_hi:[0,1]
	v_add_f32_e32 v84, v138, v85
	v_pk_fma_f32 v[82:83], v[138:139], v[138:139], v[82:83]
	v_add_f32_e32 v85, v139, v84
	v_mul_f32_e32 v84, v139, v139
	v_pk_fma_f32 v[118:119], v[236:237], s[0:1], v[90:91] op_sel_hi:[1,0,1]
	v_pk_add_f32 v[82:83], v[84:85], v[82:83] op_sel_hi:[0,1]
	v_add_f32_e32 v84, v118, v85
	v_pk_fma_f32 v[82:83], v[118:119], v[118:119], v[82:83]
	v_add_f32_e32 v85, v119, v84
	v_mul_f32_e32 v84, v119, v119
	v_pk_fma_f32 v[130:131], v[238:239], s[0:1], v[92:93] op_sel_hi:[1,0,1]
	v_pk_add_f32 v[82:83], v[84:85], v[82:83] op_sel_hi:[0,1]
	v_add_f32_e32 v84, v130, v85
	v_pk_fma_f32 v[82:83], v[130:131], v[130:131], v[82:83]
	v_add_f32_e32 v90, v131, v84
	v_mul_f32_e32 v84, v131, v131
	v_pk_add_f32 v[86:87], v[84:85], v[82:83] op_sel_hi:[0,1]
	v_pk_fma_f32 v[108:109], v[232:233], s[0:1], v[94:95] op_sel_hi:[1,0,1]
	v_pk_fma_f32 v[120:121], v[234:235], s[0:1], v[96:97] op_sel_hi:[1,0,1]
	s_mov_b64 s[4:5], 0x20080
	v_lshl_add_u64 v[88:89], v[188:189], 0, s[4:5]
	global_load_dwordx4 v[82:85], v[88:89], off offset:48
	global_load_dwordx4 v[232:235], v[88:89], off offset:32
	global_load_dwordx4 v[236:239], v[190:191], off offset:128
	global_load_dwordx4 v[240:243], v[88:89], off offset:16
	v_add_f32_e32 v88, v108, v90
	v_pk_fma_f32 v[86:87], v[108:109], v[108:109], v[86:87]
	v_add_f32_e32 v89, v109, v88
	v_mul_f32_e32 v88, v109, v109
	v_pk_add_f32 v[86:87], v[88:89], v[86:87] op_sel_hi:[0,1]
	v_add_f32_e32 v88, v120, v89
	v_pk_fma_f32 v[86:87], v[120:121], v[120:121], v[86:87]
	v_add_f32_e32 v89, v121, v88
	v_mul_f32_e32 v88, v121, v121
	v_pk_add_f32 v[86:87], v[88:89], v[86:87] op_sel_hi:[0,1]
	s_waitcnt vmcnt(8)
	v_pk_fma_f32 v[106:107], v[122:123], s[0:1], v[34:35] op_sel_hi:[1,0,1]
	v_pk_fma_f32 v[124:125], v[124:125], s[0:1], v[36:37] op_sel_hi:[1,0,1]
	v_add_f32_e32 v88, v106, v89
	v_pk_fma_f32 v[34:35], v[106:107], v[106:107], v[86:87]
	v_add_f32_e32 v87, v107, v88
	v_mul_f32_e32 v86, v107, v107
	v_add_f32_e32 v36, v124, v87
	v_pk_add_f32 v[34:35], v[86:87], v[34:35] op_sel_hi:[0,1]
	v_add_f32_e32 v36, v125, v36
	v_pk_fma_f32 v[104:105], v[166:167], s[0:1], v[38:39] op_sel_hi:[1,0,1]
	v_pk_fma_f32 v[34:35], v[124:125], v[124:125], v[34:35]
	v_add_f32_e32 v39, v104, v36
	v_mul_f32_e32 v38, v125, v125
	v_mov_b32_e32 v36, v104
	v_mov_b32_e32 v37, v125
	v_pk_add_f32 v[34:35], v[38:39], v[34:35] op_sel_hi:[0,1]
	v_pk_fma_f32 v[34:35], v[36:37], v[36:37], v[34:35]
	v_add_f32_e32 v36, v105, v39
	v_pk_fma_f32 v[122:123], v[168:169], s[0:1], v[40:41] op_sel_hi:[1,0,1]
	v_mul_f32_e32 v38, v105, v105
	v_add_f32_e32 v39, v122, v36
	v_mov_b32_e32 v36, v122
	v_mov_b32_e32 v37, v105
	v_pk_add_f32 v[34:35], v[38:39], v[34:35] op_sel_hi:[0,1]
	v_pk_fma_f32 v[34:35], v[36:37], v[36:37], v[34:35]
	v_add_f32_e32 v36, v123, v39
	v_pk_fma_f32 v[96:97], v[248:249], s[0:1], v[42:43] op_sel_hi:[1,0,1]
	v_mul_f32_e32 v38, v123, v123
	v_add_f32_e32 v39, v96, v36
	v_mov_b32_e32 v36, v96
	v_mov_b32_e32 v37, v123
	v_pk_add_f32 v[34:35], v[38:39], v[34:35] op_sel_hi:[0,1]
	v_pk_fma_f32 v[34:35], v[36:37], v[36:37], v[34:35]
	v_add_f32_e32 v36, v97, v39
	v_pk_fma_f32 v[110:111], v[250:251], s[0:1], v[44:45] op_sel_hi:[1,0,1]
	v_mul_f32_e32 v38, v97, v97
	v_add_f32_e32 v39, v110, v36
	v_mov_b32_e32 v36, v110
	v_mov_b32_e32 v37, v97
	v_pk_add_f32 v[34:35], v[38:39], v[34:35] op_sel_hi:[0,1]
	v_pk_fma_f32 v[102:103], v[114:115], s[0:1], v[46:47] op_sel_hi:[1,0,1]
	v_pk_fma_f32 v[112:113], v[116:117], s[0:1], v[48:49] op_sel_hi:[1,0,1]
	v_pk_fma_f32 v[34:35], v[36:37], v[36:37], v[34:35]
	v_add_f32_e32 v86, v111, v39
	v_mul_f32_e32 v38, v111, v111
	v_mov_b32_e32 v42, v112
	v_mov_b32_e32 v43, v103
	v_mov_b32_e32 v36, v102
	v_mov_b32_e32 v37, v111
	v_pk_add_f32 v[34:35], v[38:39], v[34:35] op_sel_hi:[0,1]
	v_pk_mul_f32 v[114:115], v[112:113], v[112:113]
	s_mov_b64 s[4:5], 0x20100
	v_lshl_add_u64 v[44:45], v[188:189], 0, s[4:5]
	global_load_dwordx4 v[166:169], v[44:45], off offset:48
	global_load_dwordx4 v[244:247], v[44:45], off offset:32
	global_load_dwordx4 v[38:41], v[190:191], off offset:256
	global_load_dwordx4 v[248:251], v[44:45], off offset:16
	v_add_f32_e32 v44, v102, v86
	v_add_f32_e32 v44, v103, v44
	v_add_f32_e32 v114, v112, v44
	s_waitcnt vmcnt(11)
	v_pk_fma_f32 v[92:93], v[194:195], s[0:1], v[66:67] op_sel_hi:[1,0,1]
	v_pk_fma_f32 v[94:95], v[196:197], s[0:1], v[68:69] op_sel_hi:[1,0,1]
	v_add_f32_e32 v44, 0, v92
	v_add_f32_e32 v46, v93, v44
	v_mul_f32_e32 v44, v93, v93
	v_pk_fma_f32 v[44:45], v[92:93], v[92:93], v[44:45] op_sel_hi:[1,1,0]
	v_add_f32_e32 v46, v94, v46
	v_pk_fma_f32 v[44:45], v[94:95], v[94:95], v[44:45]
	v_add_f32_e32 v47, v95, v46
	v_mul_f32_e32 v46, v95, v95
	s_waitcnt vmcnt(8)
; #define RL_LOAD(XV, G) { constexpr int mt__ = (G) >> 2, half__ = ((G) >> 1) & 1, nt__ = (G) & 1; \
;     _Pragma("unroll") for (int gq = 0; gq < 4; ++gq) XV[gq] = *(const f32x4*)(xin + rbase + (size_t)mt__ * 32 * 1024 + half__ * 64 + nt__ * 32 + 4 * gq); }
; #define RL_FOLD(XV, G, SM, SQ) { constexpr int mt__ = (G) >> 2, half__ = ((G) >> 1) & 1, nt__ = (G) & 1; \
;     _Pragma("unroll") for (int gq = 0; gq < 4; ++gq) _Pragma("unroll") for (int jj = 0; jj < 4; ++jj) { \
;       const float y = ALPHA * XV[gq][jj] + acc[half__][nt__][mt__][4 * gq + jj]; acc[half__][nt__][mt__][4 * gq + jj] = y; SM += y; SQ += y * y; } }
; #define SB __builtin_amdgcn_sched_barrier(0)
;   DI void full(const int mt_, const int nt_, f32x16 (&acc)[2][2][2], const int tw, const int fw, const int r, const int hh, char* lds, const int tid) const {
;     ...
;     RL_FOLD(xa, 3, sm0, sq0); SB; RL_LOAD(xa, 6); SB;
;     RL_FOLD(xc, 4, sm1, sq1); SB; RL_LOAD(xc, 7); SB;
;     RL_FOLD(xe, 5, sm1, sq1); SB;
;     RL_FOLD(xa, 6, sm1, sq1); SB;
;     RL_FOLD(xc, 7, sm1, sq1);
	v_pk_fma_f32 v[88:89], v[228:229], s[0:1], v[70:71] op_sel_hi:[1,0,1]
	v_pk_add_f32 v[44:45], v[46:47], v[44:45] op_sel_hi:[0,1]
	v_add_f32_e32 v46, v88, v47
	v_pk_fma_f32 v[44:45], v[88:89], v[88:89], v[44:45]
	v_add_f32_e32 v47, v89, v46
	v_mul_f32_e32 v46, v89, v89
	v_pk_fma_f32 v[90:91], v[230:231], s[0:1], v[72:73] op_sel_hi:[1,0,1]
	v_pk_add_f32 v[44:45], v[46:47], v[44:45] op_sel_hi:[0,1]
	v_add_f32_e32 v46, v90, v47
	v_pk_fma_f32 v[44:45], v[90:91], v[90:91], v[44:45]
	v_add_f32_e32 v47, v91, v46
	v_mul_f32_e32 v46, v91, v91
	v_pk_fma_f32 v[86:87], v[202:203], s[0:1], v[74:75] op_sel_hi:[1,0,1]
	v_pk_add_f32 v[44:45], v[46:47], v[44:45] op_sel_hi:[0,1]
	v_add_f32_e32 v46, v86, v47
	v_pk_fma_f32 v[44:45], v[86:87], v[86:87], v[44:45]
	v_add_f32_e32 v47, v87, v46
	v_mul_f32_e32 v46, v87, v87
	v_pk_fma_f32 v[76:77], v[204:205], s[0:1], v[76:77] op_sel_hi:[1,0,1]
	v_pk_add_f32 v[44:45], v[46:47], v[44:45] op_sel_hi:[0,1]
	v_add_f32_e32 v46, v76, v47
	v_pk_fma_f32 v[44:45], v[76:77], v[76:77], v[44:45]
	v_add_f32_e32 v47, v77, v46
	v_mul_f32_e32 v46, v77, v77
	v_pk_fma_f32 v[34:35], v[36:37], v[36:37], v[34:35]
	v_mul_f32_e32 v36, v103, v103
	v_pk_add_f32 v[44:45], v[46:47], v[44:45] op_sel_hi:[0,1]
	v_pk_fma_f32 v[74:75], v[98:99], s[0:1], v[78:79] op_sel_hi:[1,0,1]
	v_pk_fma_f32 v[72:73], v[100:101], s[0:1], v[80:81] op_sel_hi:[1,0,1]
	v_pk_add_f32 v[34:35], v[36:37], v[34:35] op_sel_hi:[0,1]
	v_pk_fma_f32 v[78:79], v[42:43], v[42:43], v[34:35]
	s_mov_b64 s[4:5], 0x20180
	v_lshl_add_u64 v[42:43], v[188:189], 0, s[4:5]
	global_load_dwordx4 v[34:37], v[42:43], off offset:48
	global_load_dwordx4 v[98:101], v[42:43], off offset:32
	s_nop 0
	global_load_dwordx4 v[188:191], v[190:191], off offset:384
	s_nop 0
	global_load_dwordx4 v[194:197], v[42:43], off offset:16
	v_add_f32_e32 v46, v74, v47
	v_pk_fma_f32 v[42:43], v[74:75], v[74:75], v[44:45]
	v_add_f32_e32 v45, v75, v46
	v_mul_f32_e32 v44, v75, v75
	v_pk_add_f32 v[42:43], v[44:45], v[42:43] op_sel_hi:[0,1]
	v_add_f32_e32 v44, v72, v45
	v_pk_fma_f32 v[42:43], v[72:73], v[72:73], v[42:43]
	v_add_f32_e32 v45, v73, v44
	v_mul_f32_e32 v44, v73, v73
	v_pk_add_f32 v[42:43], v[44:45], v[42:43] op_sel_hi:[0,1]
	s_waitcnt vmcnt(9)
	v_pk_fma_f32 v[66:67], v[236:237], s[0:1], v[50:51] op_sel_hi:[1,0,1]
	v_pk_fma_f32 v[70:71], v[238:239], s[0:1], v[52:53] op_sel_hi:[1,0,1]
	v_add_f32_e32 v44, v66, v45
	v_pk_fma_f32 v[42:43], v[66:67], v[66:67], v[42:43]
	v_add_f32_e32 v45, v67, v44
	v_mul_f32_e32 v44, v67, v67
	v_pk_add_f32 v[42:43], v[44:45], v[42:43] op_sel_hi:[0,1]
	v_add_f32_e32 v44, v70, v45
	v_pk_fma_f32 v[42:43], v[70:71], v[70:71], v[42:43]
	v_add_f32_e32 v45, v71, v44
	v_mul_f32_e32 v44, v71, v71
	s_waitcnt vmcnt(8)
	v_pk_fma_f32 v[54:55], v[240:241], s[0:1], v[54:55] op_sel_hi:[1,0,1]
	v_pk_add_f32 v[42:43], v[44:45], v[42:43] op_sel_hi:[0,1]
	v_add_f32_e32 v44, v54, v45
	v_pk_fma_f32 v[42:43], v[54:55], v[54:55], v[42:43]
	v_add_f32_e32 v45, v55, v44
	v_mul_f32_e32 v44, v55, v55
	v_pk_fma_f32 v[68:69], v[242:243], s[0:1], v[56:57] op_sel_hi:[1,0,1]
	v_pk_add_f32 v[42:43], v[44:45], v[42:43] op_sel_hi:[0,1]
	v_add_f32_e32 v44, v68, v45
	v_pk_fma_f32 v[42:43], v[68:69], v[68:69], v[42:43]
	v_add_f32_e32 v45, v69, v44
	v_mul_f32_e32 v44, v69, v69
	v_pk_fma_f32 v[50:51], v[232:233], s[0:1], v[58:59] op_sel_hi:[1,0,1]
	v_pk_add_f32 v[42:43], v[44:45], v[42:43] op_sel_hi:[0,1]
	v_add_f32_e32 v44, v50, v45
	v_pk_fma_f32 v[42:43], v[50:51], v[50:51], v[42:43]
	v_add_f32_e32 v45, v51, v44
	v_mul_f32_e32 v44, v51, v51
	v_pk_fma_f32 v[56:57], v[234:235], s[0:1], v[60:61] op_sel_hi:[1,0,1]
	v_pk_add_f32 v[42:43], v[44:45], v[42:43] op_sel_hi:[0,1]
	v_add_f32_e32 v44, v56, v45
	v_pk_fma_f32 v[42:43], v[56:57], v[56:57], v[42:43]
	v_add_f32_e32 v45, v57, v44
	v_mul_f32_e32 v44, v57, v57
	v_pk_fma_f32 v[48:49], v[82:83], s[0:1], v[62:63] op_sel_hi:[1,0,1]
	v_pk_add_f32 v[42:43], v[44:45], v[42:43] op_sel_hi:[0,1]
	v_add_f32_e32 v44, v48, v45
	v_pk_fma_f32 v[42:43], v[48:49], v[48:49], v[42:43]
	v_add_f32_e32 v45, v49, v44
	v_mul_f32_e32 v44, v49, v49
	v_pk_fma_f32 v[52:53], v[84:85], s[0:1], v[64:65] op_sel_hi:[1,0,1]
	v_pk_add_f32 v[42:43], v[44:45], v[42:43] op_sel_hi:[0,1]
	v_add_f32_e32 v44, v52, v45
	v_pk_fma_f32 v[42:43], v[52:53], v[52:53], v[42:43]
	v_add_f32_e32 v46, v53, v44
	v_mul_f32_e32 v44, v53, v53
	v_pk_add_f32 v[44:45], v[44:45], v[42:43] op_sel_hi:[0,1]
	s_waitcnt vmcnt(5)
	v_pk_fma_f32 v[42:43], v[38:39], s[0:1], v[18:19] op_sel_hi:[1,0,1]
	v_pk_fma_f32 v[26:27], v[244:245], s[0:1], v[26:27] op_sel_hi:[1,0,1]
	v_add_f32_e32 v38, v42, v46
	v_pk_fma_f32 v[18:19], v[42:43], v[42:43], v[44:45]
	v_add_f32_e32 v39, v43, v38
	v_mul_f32_e32 v38, v43, v43
	v_pk_fma_f32 v[46:47], v[40:41], s[0:1], v[20:21] op_sel_hi:[1,0,1]
	v_pk_add_f32 v[18:19], v[38:39], v[18:19] op_sel_hi:[0,1]
	v_add_f32_e32 v20, v46, v39
	v_pk_fma_f32 v[18:19], v[46:47], v[46:47], v[18:19]
	v_add_f32_e32 v21, v47, v20
	v_mul_f32_e32 v20, v47, v47
	s_waitcnt vmcnt(4)
; #define RL_LOAD(XV, G) { constexpr int mt__ = (G) >> 2, half__ = ((G) >> 1) & 1, nt__ = (G) & 1; \
;     _Pragma("unroll") for (int gq = 0; gq < 4; ++gq) XV[gq] = *(const f32x4*)(xin + rbase + (size_t)mt__ * 32 * 1024 + half__ * 64 + nt__ * 32 + 4 * gq); }
; #define RL_FOLD(XV, G, SM, SQ) { constexpr int mt__ = (G) >> 2, half__ = ((G) >> 1) & 1, nt__ = (G) & 1; \
;     _Pragma("unroll") for (int gq = 0; gq < 4; ++gq) _Pragma("unroll") for (int jj = 0; jj < 4; ++jj) { \
;       const float y = ALPHA * XV[gq][jj] + acc[half__][nt__][mt__][4 * gq + jj]; acc[half__][nt__][mt__][4 * gq + jj] = y; SM += y; SQ += y * y; } }
; #define SB __builtin_amdgcn_sched_barrier(0)
;   DI void full(const int mt_, const int nt_, f32x16 (&acc)[2][2][2], const int tw, const int fw, const int r, const int hh, char* lds, const int tid) const {
;     ...
;     float sm0 = 0.f, sq0 = 0.f, sm1 = 0.f, sq1 = 0.f;
;     RL_LOAD(xa, 0); RL_LOAD(xc, 1); RL_LOAD(xe, 2); SB;
;     RL_FOLD(xa, 0, sm0, sq0); SB; RL_LOAD(xa, 3); SB;
;     RL_FOLD(xc, 1, sm0, sq0); SB; RL_LOAD(xc, 4); SB;
;     RL_FOLD(xe, 2, sm0, sq0); SB; RL_LOAD(xe, 5); SB;
;     RL_FOLD(xa, 3, sm0, sq0); SB; RL_LOAD(xa, 6); SB;
;     RL_FOLD(xc, 4, sm1, sq1); SB; RL_LOAD(xc, 7); SB;
;     RL_FOLD(xe, 5, sm1, sq1); SB;
;     RL_FOLD(xa, 6, sm1, sq1); SB;
;     RL_FOLD(xc, 7, sm1, sq1);
;     ...
;     sm0 += __shfl_xor(sm0, 32, 64); sq0 += __shfl_xor(sq0, 32, 64); sm1 += __shfl_xor(sm1, 32, 64); sq1 += __shfl_xor(sq1, 32, 64);
;     if (hh == 0) {
;       float* pp = part + ((fw * 256) + tw * 64 + r) * 2; pp[0] = sm0; pp[1] = sq0;
;       pp[64] = sm1; pp[65] = sq1;
	v_pk_fma_f32 v[38:39], v[248:249], s[0:1], v[22:23] op_sel_hi:[1,0,1]
	v_pk_add_f32 v[18:19], v[20:21], v[18:19] op_sel_hi:[0,1]
	v_add_f32_e32 v20, v38, v21
	v_pk_fma_f32 v[18:19], v[38:39], v[38:39], v[18:19]
	v_add_f32_e32 v21, v39, v20
	v_mul_f32_e32 v20, v39, v39
	v_pk_fma_f32 v[44:45], v[250:251], s[0:1], v[24:25] op_sel_hi:[1,0,1]
	v_pk_add_f32 v[18:19], v[20:21], v[18:19] op_sel_hi:[0,1]
	v_add_f32_e32 v20, v44, v21
	v_pk_fma_f32 v[18:19], v[44:45], v[44:45], v[18:19]
	v_add_f32_e32 v21, v45, v20
	v_mul_f32_e32 v20, v45, v45
	v_pk_add_f32 v[18:19], v[20:21], v[18:19] op_sel_hi:[0,1]
	v_add_f32_e32 v20, v26, v21
	v_pk_fma_f32 v[18:19], v[26:27], v[26:27], v[18:19]
	v_add_f32_e32 v21, v27, v20
	v_mul_f32_e32 v20, v27, v27
	v_pk_fma_f32 v[40:41], v[246:247], s[0:1], v[28:29] op_sel_hi:[1,0,1]
	v_pk_add_f32 v[18:19], v[20:21], v[18:19] op_sel_hi:[0,1]
	v_add_f32_e32 v20, v40, v21
	v_pk_fma_f32 v[18:19], v[40:41], v[40:41], v[18:19]
	v_add_f32_e32 v21, v41, v20
	v_mul_f32_e32 v20, v41, v41
	v_pk_fma_f32 v[24:25], v[166:167], s[0:1], v[30:31] op_sel_hi:[1,0,1]
	v_pk_add_f32 v[18:19], v[20:21], v[18:19] op_sel_hi:[0,1]
	v_add_f32_e32 v20, v24, v21
	v_pk_fma_f32 v[18:19], v[24:25], v[24:25], v[18:19]
	v_add_f32_e32 v21, v25, v20
	v_mul_f32_e32 v20, v25, v25
	v_pk_fma_f32 v[28:29], v[168:169], s[0:1], v[32:33] op_sel_hi:[1,0,1]
	v_pk_add_f32 v[18:19], v[20:21], v[18:19] op_sel_hi:[0,1]
	v_add_f32_e32 v20, v28, v21
	v_pk_fma_f32 v[18:19], v[28:29], v[28:29], v[18:19]
	v_add_f32_e32 v22, v29, v20
	v_mul_f32_e32 v20, v29, v29
	v_pk_add_f32 v[20:21], v[20:21], v[18:19] op_sel_hi:[0,1]
	s_waitcnt vmcnt(1)
	v_pk_fma_f32 v[18:19], v[188:189], s[0:1], v[2:3] op_sel_hi:[1,0,1]
	s_waitcnt vmcnt(0)
	v_pk_fma_f32 v[6:7], v[194:195], s[0:1], v[6:7] op_sel_hi:[1,0,1]
	v_add_f32_e32 v22, v18, v22
	v_pk_fma_f32 v[2:3], v[18:19], v[18:19], v[20:21]
	v_add_f32_e32 v21, v19, v22
	v_pk_fma_f32 v[22:23], v[190:191], s[0:1], v[4:5] op_sel_hi:[1,0,1]
	v_mul_f32_e32 v20, v19, v19
	v_add_f32_e32 v4, v22, v21
	v_pk_add_f32 v[2:3], v[20:21], v[2:3] op_sel_hi:[0,1]
	v_add_f32_e32 v4, v23, v4
	v_pk_fma_f32 v[2:3], v[22:23], v[22:23], v[2:3]
	v_add_f32_e32 v21, v6, v4
	v_mul_f32_e32 v20, v23, v23
	v_mov_b32_e32 v4, v6
	v_mov_b32_e32 v5, v23
	v_pk_add_f32 v[2:3], v[20:21], v[2:3] op_sel_hi:[0,1]
	v_pk_fma_f32 v[2:3], v[4:5], v[4:5], v[2:3]
	v_add_f32_e32 v4, v7, v21
	v_pk_fma_f32 v[20:21], v[196:197], s[0:1], v[8:9] op_sel_hi:[1,0,1]
	v_mul_f32_e32 v8, v7, v7
	v_add_f32_e32 v9, v20, v4
	v_mov_b32_e32 v4, v20
	v_mov_b32_e32 v5, v7
	v_pk_add_f32 v[2:3], v[8:9], v[2:3] op_sel_hi:[0,1]
	v_pk_fma_f32 v[4:5], v[4:5], v[4:5], v[2:3]
	v_add_f32_e32 v8, v21, v9
	v_pk_fma_f32 v[2:3], v[98:99], s[0:1], v[10:11] op_sel_hi:[1,0,1]
	v_mul_f32_e32 v10, v21, v21
	v_add_f32_e32 v11, v2, v8
	v_mov_b32_e32 v8, v2
	v_mov_b32_e32 v9, v21
	v_pk_add_f32 v[4:5], v[10:11], v[4:5] op_sel_hi:[0,1]
	v_pk_fma_f32 v[4:5], v[8:9], v[8:9], v[4:5]
	v_add_f32_e32 v10, v3, v11
	v_pk_fma_f32 v[8:9], v[100:101], s[0:1], v[12:13] op_sel_hi:[1,0,1]
	v_mul_f32_e32 v12, v3, v3
	v_add_f32_e32 v13, v8, v10
	v_mov_b32_e32 v10, v8
	v_mov_b32_e32 v11, v3
	v_pk_add_f32 v[4:5], v[12:13], v[4:5] op_sel_hi:[0,1]
	v_pk_fma_f32 v[10:11], v[10:11], v[10:11], v[4:5]
	v_add_f32_e32 v12, v9, v13
	v_pk_fma_f32 v[4:5], v[34:35], s[0:1], v[14:15] op_sel_hi:[1,0,1]
	v_mul_f32_e32 v14, v9, v9
	v_add_f32_e32 v15, v4, v12
	v_mov_b32_e32 v12, v4
	v_mov_b32_e32 v13, v9
	v_pk_add_f32 v[10:11], v[14:15], v[10:11] op_sel_hi:[0,1]
	v_pk_fma_f32 v[12:13], v[12:13], v[12:13], v[10:11]
	v_pk_fma_f32 v[10:11], v[36:37], s[0:1], v[16:17] op_sel_hi:[1,0,1]
	v_mul_f32_e32 v30, v5, v5
	v_mov_b32_e32 v16, v10
	v_mov_b32_e32 v17, v5
	v_pk_add_f32 v[12:13], v[30:31], v[12:13] op_sel_hi:[0,1]
	v_pk_fma_f32 v[12:13], v[16:17], v[16:17], v[12:13]
	v_pk_mul_f32 v[16:17], v[10:11], v[10:11]
	v_add_f32_e32 v14, v5, v15
	v_mov_b32_e32 v15, v17
	v_add_f32_e32 v14, v10, v14
	v_pk_mov_b32 v[12:13], v[10:11], v[12:13] op_sel:[1,0]
	v_pk_add_f32 v[12:13], v[12:13], v[14:15]
	v_pk_mov_b32 v[14:15], v[112:113], v[78:79] op_sel:[1,0]
	v_pk_add_f32 v[14:15], v[14:15], v[114:115]
	v_mov_b32_e32 v16, v14
	v_mov_b32_e32 v17, v15
	v_mov_b32_e32 v30, v12
	v_mov_b32_e32 v31, v13
	s_nop 1
	v_permlane32_swap_b32_e32 v16, v14
	v_permlane32_swap_b32_e32 v17, v15
	v_permlane32_swap_b32_e32 v30, v12
	v_permlane32_swap_b32_e32 v31, v13
	v_cmp_eq_u32_e32 vcc, 0, v226
	s_and_saveexec_b64 s[4:5], vcc
	s_cbranch_execz .LBB0_772
	v_lshlrev_b32_e32 v32, 3, v186
	v_and_b32_e32 v32, 0xfffffef8, v32
	v_add_u32_e32 v32, 0, v32
	v_add_u32_e32 v32, 0x12000, v32
	s_waitcnt lgkmcnt(2)
	v_pk_add_f32 v[14:15], v[14:15], v[16:17]
	s_waitcnt lgkmcnt(0)
	v_pk_add_f32 v[12:13], v[12:13], v[30:31]
	ds_write2_b64 v32, v[14:15], v[12:13] offset1:32
